# dead-code cleanup in the P5 head loop: 28 instructions whose results are unused after the earlier rewrites (param address chain, spill reloads, two vcc set-ups); on top of all11
# speedup vs baseline: 1.0217x; 1.0033x over previous
; #define LAS __attribute__((address_space(3)))
; #define LBAR() asm volatile("s_waitcnt lgkmcnt(0)\n\ts_barrier" ::: "memory")
; __device__ __forceinline__ void rwkv_chunk_group(Frame& F, int bc, unsigned long long& tsub) {
;     ...
;         asm volatile("s_waitcnt vmcnt(0)" ::: "memory"); LBAR();
;         f32x4 aw[2], aa[2], ag[2];
; #pragma unroll
;         for (int q = 0; q < 2; ++q) { const int n0 = 16 * ((2 * w + q) & 3); aw[q] = Z4; aa[q] = Z4; ag[q] = Z4;
;             const LAS unsigned char* wp = L + L_LWA + (n0 + fr) * 128 + fq * 16; const LAS unsigned char* gp = L + L_LG + (n0 + fr) * 64 + fq * 16;
; #pragma unroll
;             for (int k = 0; k < 2; ++k) { aw[q] = __builtin_amdgcn_mfma_f32_16x16x32_bf16(xw[k], *(const LAS bf16x8*)(wp + k * 64), aw[q], 0, 0, 0); aa[q] = __builtin_amdgcn_mfma_f32_16x16x32_bf16(xa[k], *(const LAS bf16x8*)(wp + 8192 + k * 64), aa[q], 0, 0, 0); }
; #pragma unroll
;             for (int k = 0; k < 5; ++k) ag[q] = __builtin_amdgcn_mfma_f32_16x16x32_bf16(xg[k], *(const LAS bf16x8*)(gp + k * 4096), ag[q], 0, 0, 0);
;         }
;     ...
;         const int gc = h * 64 + ch;
;         const float mur = mu[gc], muk = mu[512 + gc], muv = mu[1024 + gc];
;         const float w0 = (PRM + 2048)[gc], a0 = (PRM + 2560)[gc], k_k = (PRM + 3072)[gc], k_a = (PRM + 3584)[gc], r_k = (PRM + 4096)[gc];
.LBB0_1412:
	s_waitcnt vmcnt(8)
	v_perm_b32 v160, v203, v202, s5
	v_perm_b32 v161, v216, v215, s5
	v_perm_b32 v166, v204, v203, s5
	v_perm_b32 v167, v217, v216, s5
	v_perm_b32 v168, v206, v205, s5
	v_perm_b32 v169, v219, v218, s5
	v_perm_b32 v170, v212, v207, s5
	v_perm_b32 v171, v221, v220, s5
	v_perm_b32 v165, v214, v213, s5
	v_perm_b32 v172, v223, v222, s5
	v_readlane_b32 s98, v254, 2
	v_readlane_b32 s100, v254, 20
	v_readlane_b32 s101, v254, 21
	s_add_i32 s98, s98, s12
	s_lshl_b32 s98, s98, 6
	s_and_b32 s98, s98, 0x1c0
	v_add_lshl_u32 v238, v208, s98, 2
	v_mov_b32_e32 v239, 0
	s_nop 0
	v_lshl_add_u64 v[232:233], s[100:101], 0, v[238:239]
	s_mov_b64 s[100:101], 0x2000
	v_lshl_add_u64 v[234:235], v[232:233], 0, s[100:101]
	s_mov_b64 s[100:101], 0x3800
	v_lshl_add_u64 v[236:237], v[232:233], 0, s[100:101]
	global_load_dword v224, v[232:233], off
	global_load_dword v225, v[232:233], off offset:2048
	global_load_dword v226, v[234:235], off offset:-4096
	global_load_dword v227, v[234:235], off
	global_load_dword v228, v[234:235], off offset:2048
	global_load_dword v229, v[236:237], off offset:-2048
	global_load_dword v230, v[236:237], off
	global_load_dword v231, v[236:237], off offset:2048
	s_waitcnt lgkmcnt(0)
	s_barrier
	v_xor_b32_e32 v102, 64, v137
	v_xor_b32_e32 v103, 64, v139
	ds_read_b128 v[36:39], v137
	ds_read_b128 v[76:79], v139
	ds_read_b128 v[98:101], v102
	ds_read_b128 v[174:177], v103
	ds_read_b128 v[40:43], v137 offset:8192
	ds_read_b128 v[80:83], v139 offset:8192
	ds_read_b128 v[178:181], v102 offset:8192
	ds_read_b128 v[182:185], v103 offset:8192
	ds_read_b128 v[44:47], v138
	ds_read_b128 v[84:87], v140
	ds_read_b128 v[186:189], v138 offset:4096
	ds_read_b128 v[232:235], v140 offset:4096
	ds_read_b128 v[236:239], v138 offset:8192
	ds_read_b128 v[240:243], v140 offset:8192
	ds_read_b128 v[244:247], v138 offset:12288
	s_waitcnt lgkmcnt(14)
	v_mfma_f32_16x16x32_bf16 v[36:39], v[0:3], v[36:39], 0
	ds_read_b128 v[248:251], v140 offset:12288
	v_add_u32_e32 v52, s33, v111
	s_mov_b32 s68, s12
	s_waitcnt lgkmcnt(14)
	v_mfma_f32_16x16x32_bf16 v[76:79], v[0:3], v[76:79], 0
	ds_read_b128 v[88:91], v138 offset:16384
	v_readlane_b32 s12, v254, 2
	s_add_i32 s14, s68, s12
	s_waitcnt lgkmcnt(14)
	v_mfma_f32_16x16x32_bf16 v[36:39], v[4:7], v[98:101], v[36:39]
	ds_read_b128 v[98:101], v140 offset:16384
	s_lshl_b32 s14, s14, 6
	s_waitcnt lgkmcnt(14)
	v_mfma_f32_16x16x32_bf16 v[76:79], v[4:7], v[174:177], v[76:79]
	s_and_b32 s14, s14, 0x1c0
	s_waitcnt lgkmcnt(13)
	v_mfma_f32_16x16x32_bf16 v[40:43], v[8:11], v[40:43], 0
	s_add_i32 s66, s11, s14
	s_waitcnt lgkmcnt(12)
	v_mfma_f32_16x16x32_bf16 v[80:83], v[8:11], v[80:83], 0
	v_add_u32_e32 v191, s6, v125
	s_waitcnt lgkmcnt(11)
	v_mfma_f32_16x16x32_bf16 v[40:43], v[12:15], v[178:181], v[40:43]

; #define LAS __attribute__((address_space(3)))
; #define LBAR() asm volatile("s_waitcnt lgkmcnt(0)\n\ts_barrier" ::: "memory")
; __device__ __forceinline__ void rwkv_chunk_group(Frame& F, int bc, unsigned long long& tsub) {
;     ...
;         for (int q = 0; q < 2; ++q) { const int n0 = 16 * ((2 * w + q) & 3); aw[q] = Z4; aa[q] = Z4; ag[q] = Z4;
;             const LAS unsigned char* wp = L + L_LWA + (n0 + fr) * 128 + fq * 16; const LAS unsigned char* gp = L + L_LG + (n0 + fr) * 64 + fq * 16;
; #pragma unroll
;             for (int k = 0; k < 2; ++k) { aw[q] = __builtin_amdgcn_mfma_f32_16x16x32_bf16(xw[k], *(const LAS bf16x8*)(wp + k * 64), aw[q], 0, 0, 0); aa[q] = __builtin_amdgcn_mfma_f32_16x16x32_bf16(xa[k], *(const LAS bf16x8*)(wp + 8192 + k * 64), aa[q], 0, 0, 0); }
; #pragma unroll
;             for (int k = 0; k < 5; ++k) ag[q] = __builtin_amdgcn_mfma_f32_16x16x32_bf16(xg[k], *(const LAS bf16x8*)(gp + k * 4096), ag[q], 0, 0, 0);
;         }
;         LBAR();
; #pragma unroll
;         for (int q = 0; q < 2; ++q) { const int tw = 2 * w + q, m0 = 16 * (tw >> 2), n0 = 16 * (tw & 3);
; #pragma unroll
;             for (int v = 0; v < 4; ++v) { const int t = m0 + 4 * fq + v, cc = n0 + fr;
;                 *(LAS float*)(L + L_WL + (t * 65 + cc) * 4) = aw[q][v]; *(LAS float*)(L + L_AL + (t * 65 + cc) * 4) = aa[q][v]; *(LAS float*)(L + L_GL + (t * 65 + cc) * 4) = ag[q][v]; } }
;         LBAR();
	s_waitcnt lgkmcnt(10)
	v_mfma_f32_16x16x32_bf16 v[80:83], v[12:15], v[182:185], v[80:83]
	s_mov_b32 s64, s12
	s_waitcnt lgkmcnt(9)
	v_mfma_f32_16x16x32_bf16 v[44:47], v[16:19], v[44:47], 0
	s_add_i32 s12, s68, 1
	s_waitcnt lgkmcnt(8)
	v_mfma_f32_16x16x32_bf16 v[84:87], v[16:19], v[84:87], 0
	s_add_i32 s13, s12, s64
	s_waitcnt lgkmcnt(7)
	v_mfma_f32_16x16x32_bf16 v[44:47], v[20:23], v[186:189], v[44:47]
	v_add_u32_e32 v96, s6, v124
	s_waitcnt lgkmcnt(6)
	v_mfma_f32_16x16x32_bf16 v[84:87], v[20:23], v[232:235], v[84:87]
	v_add_u32_e32 v93, s7, v123
	s_waitcnt lgkmcnt(5)
	v_mfma_f32_16x16x32_bf16 v[44:47], v[24:27], v[236:239], v[44:47]
	v_add_u32_e32 v97, s7, v124
	s_waitcnt lgkmcnt(4)
	v_mfma_f32_16x16x32_bf16 v[84:87], v[24:27], v[240:243], v[84:87]
	v_add_u32_e32 v192, s7, v125
	s_waitcnt lgkmcnt(3)
	v_mfma_f32_16x16x32_bf16 v[44:47], v[28:31], v[244:247], v[44:47]
	v_lshlrev_b32_e32 v197, 16, v162
	s_waitcnt lgkmcnt(2)
	v_mfma_f32_16x16x32_bf16 v[84:87], v[28:31], v[248:251], v[84:87]
	v_and_b32_e32 v199, 0xffff0000, v172
	s_waitcnt lgkmcnt(1)
	v_mfma_f32_16x16x32_bf16 v[44:47], v[32:35], v[88:91], v[44:47]
	s_ashr_i32 s67, s66, 31
	s_waitcnt lgkmcnt(0)
	v_mfma_f32_16x16x32_bf16 v[84:87], v[32:35], v[98:101], v[84:87]
	s_and_b32 s13, s13, 7
	s_nop 7
	s_nop 7
	s_waitcnt lgkmcnt(0)
	s_barrier
	ds_write_b32 v52, v36
	v_add_u32_e32 v36, s6, v111
	ds_write_b32 v36, v40
	v_add_u32_e32 v36, s7, v111
	ds_write_b32 v36, v44
	v_add_u32_e32 v36, s33, v112
	ds_write_b32 v36, v37
	v_add_u32_e32 v36, s6, v112
	ds_write_b32 v36, v41
	v_add_u32_e32 v36, s7, v112
	ds_write_b32 v36, v45
	v_add_u32_e32 v36, s33, v113
	ds_write_b32 v36, v38
	v_add_u32_e32 v36, s6, v113
	ds_write_b32 v36, v42
	v_add_u32_e32 v36, s7, v113
	ds_write_b32 v36, v46
	v_add_u32_e32 v36, s33, v114
	ds_write_b32 v36, v39
	v_add_u32_e32 v36, s6, v114
	ds_write_b32 v36, v43
	v_add_u32_e32 v36, s7, v114
	ds_write_b32 v36, v47
	v_add_u32_e32 v36, s33, v115
	ds_write_b32 v36, v76
	v_add_u32_e32 v36, s6, v115
	ds_write_b32 v36, v80
	v_add_u32_e32 v36, s7, v115
	ds_write_b32 v36, v84
	v_add_u32_e32 v36, s33, v116
	ds_write_b32 v36, v77
	v_add_u32_e32 v36, s6, v116
	ds_write_b32 v36, v81
	v_add_u32_e32 v36, s7, v116
	ds_write_b32 v36, v85
	v_add_u32_e32 v36, s33, v117
	ds_write_b32 v36, v78
	v_add_u32_e32 v36, s6, v117
	ds_write_b32 v36, v82
	v_add_u32_e32 v36, s7, v117
	ds_write_b32 v36, v86
	v_add_u32_e32 v36, s33, v118
	ds_write_b32 v36, v79
	v_add_u32_e32 v36, s6, v118
	ds_write_b32 v36, v83
	v_add_u32_e32 v36, s7, v118
	ds_write_b32 v36, v87


; #define LBAR() asm volatile("s_waitcnt lgkmcnt(0)\n\ts_barrier" ::: "memory")
; #define TSUB(k) do { } while (0)
; __device__ __forceinline__ void rwkv_chunk_group(Frame& F, int bc, unsigned long long& tsub) {
;     ...
;         LBAR();
;     }
;     TSUB(1);
;     {
;         const int gc = h * 64 + ch;
;         const float mur = mu[gc], muk = mu[512 + gc], muv = mu[1024 + gc];
;         const float w0 = (PRM + 2048)[gc], a0 = (PRM + 2560)[gc], k_k = (PRM + 3072)[gc], k_a = (PRM + 3584)[gc], r_k = (PRM + 4096)[gc];
	s_waitcnt lgkmcnt(0)
	s_barrier
	v_add_u32_e32 v41, s7, v120
	v_add_u32_e32 v87, s7, v122

; __device__ __forceinline__ void rwkv_chunk_group(Frame& F, int bc, unsigned long long& tsub) {
;     ...
;         const int gc = h * 64 + ch;
;         const float mur = mu[gc], muk = mu[512 + gc], muv = mu[1024 + gc];
;         const float w0 = (PRM + 2048)[gc], a0 = (PRM + 2560)[gc], k_k = (PRM + 3072)[gc], k_a = (PRM + 3584)[gc], r_k = (PRM + 4096)[gc];
	s_waitcnt vmcnt(0)
	v_mov_b32_e32 v95, v224
	v_mov_b32_e32 v42, v225


; __device__ __forceinline__ void rwkv_chunk_group(Frame& F, int bc, unsigned long long& tsub) {
;     ...
;         const int gc = h * 64 + ch;
;         const float mur = mu[gc], muk = mu[512 + gc], muv = mu[1024 + gc];
;         const float w0 = (PRM + 2048)[gc], a0 = (PRM + 2560)[gc], k_k = (PRM + 3072)[gc], k_a = (PRM + 3584)[gc], r_k = (PRM + 4096)[gc];
	s_nop 0


; #define LAS __attribute__((address_space(3)))
; __device__ __forceinline__ void rwkv_chunk_group(Frame& F, int bc, unsigned long long& tsub) {
;     ...
;         const int gc = h * 64 + ch;
;         const float mur = mu[gc], muk = mu[512 + gc], muv = mu[1024 + gc];
;         const float w0 = (PRM + 2048)[gc], a0 = (PRM + 2560)[gc], k_k = (PRM + 3072)[gc], k_a = (PRM + 3584)[gc], r_k = (PRM + 4096)[gc];
;         float rr[8], kp[8], vv[8], aa[8], bb[8], ld[8], vbv[8], ggv[8];
;         float pr = bf2f(raw[0][0]), pk = bf2f(raw[0][1]), pv = bf2f(raw[0][2]);
;         bf16* VBp = (bf16*)(F.ws + WS_VB) + (size_t)item * 4096; bf16* Gp = (bf16*)(F.ws + WS_G) + (size_t)item * 4096;
;         float run = 0.f; float kkv[8], icv[8], sq[8], bq[8];
; #pragma unroll
;         for (int tt = 0; tt < 8; ++tt) { const int t = tb + tt;
;             const float cr = bf2f(raw[tt + 1][0]), ck = bf2f(raw[tt + 1][1]), cv = bf2f(raw[tt + 1][2]);
;             const float r = cr + (pr - cr) * mur, k = ck + (pk - ck) * muk, v = cv + (pv - cv) * muv; pr = cr; pk = ck; pv = cv;
;             const float wl = *(const LAS float*)(L + L_WL + (t * 65 + ch) * 4), al = *(const LAS float*)(L + L_AL + (t * 65 + ch) * 4), gl = *(const LAS float*)(L + L_GL + (t * 65 + ch) * 4);
	v_mov_b32_e32 v52, v226
	v_add_u32_e32 v83, s7, v121

; __device__ __forceinline__ void rwkv_chunk_group(Frame& F, int bc, unsigned long long& tsub) {
;     ...
;         const int gc = h * 64 + ch;
;         const float mur = mu[gc], muk = mu[512 + gc], muv = mu[1024 + gc];
;         const float w0 = (PRM + 2048)[gc], a0 = (PRM + 2560)[gc], k_k = (PRM + 3072)[gc], k_a = (PRM + 3584)[gc], r_k = (PRM + 4096)[gc];
	v_mov_b32_e32 v45, v227


; __device__ __forceinline__ void rwkv_chunk_group(Frame& F, int bc, unsigned long long& tsub) {
;     ...
;         float pr = bf2f(raw[0][0]), pk = bf2f(raw[0][1]), pv = bf2f(raw[0][2]);
;         bf16* VBp = (bf16*)(F.ws + WS_VB) + (size_t)item * 4096; bf16* Gp = (bf16*)(F.ws + WS_G) + (size_t)item * 4096;
;         float run = 0.f; float kkv[8], icv[8], sq[8], bq[8];
; #pragma unroll
;         for (int tt = 0; tt < 8; ++tt) { const int t = tb + tt;
;             const float cr = bf2f(raw[tt + 1][0]), ck = bf2f(raw[tt + 1][1]), cv = bf2f(raw[tt + 1][2]);
;             const float r = cr + (pr - cr) * mur, k = ck + (pk - ck) * muk, v = cv + (pv - cv) * muv; pr = cr; pk = ck; pv = cv;
	v_lshlrev_b32_e32 v82, 16, v155
	v_and_b32_e32 v77, 0xffff0000, v167

; __device__ __forceinline__ void rwkv_chunk_group(Frame& F, int bc, unsigned long long& tsub) {
;     ...
;         const int gc = h * 64 + ch;
;         const float mur = mu[gc], muk = mu[512 + gc], muv = mu[1024 + gc];
;         const float w0 = (PRM + 2048)[gc], a0 = (PRM + 2560)[gc], k_k = (PRM + 3072)[gc], k_a = (PRM + 3584)[gc], r_k = (PRM + 4096)[gc];
	v_mov_b32_e32 v43, v228


; __device__ __forceinline__ void rwkv_chunk_group(Frame& F, int bc, unsigned long long& tsub) {
;     ...
;         float pr = bf2f(raw[0][0]), pk = bf2f(raw[0][1]), pv = bf2f(raw[0][2]);
;         bf16* VBp = (bf16*)(F.ws + WS_VB) + (size_t)item * 4096; bf16* Gp = (bf16*)(F.ws + WS_G) + (size_t)item * 4096;
;         float run = 0.f; float kkv[8], icv[8], sq[8], bq[8];
; #pragma unroll
;         for (int tt = 0; tt < 8; ++tt) { const int t = tb + tt;
;             const float cr = bf2f(raw[tt + 1][0]), ck = bf2f(raw[tt + 1][1]), cv = bf2f(raw[tt + 1][2]);
;             const float r = cr + (pr - cr) * mur, k = ck + (pk - ck) * muk, v = cv + (pv - cv) * muv; pr = cr; pk = ck; pv = cv;
	v_lshlrev_b32_e32 v76, 16, v167
	v_and_b32_e32 v79, 0xffff0000, v166


; __device__ __forceinline__ void rwkv_chunk_group(Frame& F, int bc, unsigned long long& tsub) {
;     ...
;         const int gc = h * 64 + ch;
;         const float mur = mu[gc], muk = mu[512 + gc], muv = mu[1024 + gc];
;         const float w0 = (PRM + 2048)[gc], a0 = (PRM + 2560)[gc], k_k = (PRM + 3072)[gc], k_a = (PRM + 3584)[gc], r_k = (PRM + 4096)[gc];
;         float rr[8], kp[8], vv[8], aa[8], bb[8], ld[8], vbv[8], ggv[8];
;         float pr = bf2f(raw[0][0]), pk = bf2f(raw[0][1]), pv = bf2f(raw[0][2]);
;         bf16* VBp = (bf16*)(F.ws + WS_VB) + (size_t)item * 4096; bf16* Gp = (bf16*)(F.ws + WS_G) + (size_t)item * 4096;
;         float run = 0.f; float kkv[8], icv[8], sq[8], bq[8];
; #pragma unroll
;         for (int tt = 0; tt < 8; ++tt) { const int t = tb + tt;
;             const float cr = bf2f(raw[tt + 1][0]), ck = bf2f(raw[tt + 1][1]), cv = bf2f(raw[tt + 1][2]);
;             const float r = cr + (pr - cr) * mur, k = ck + (pk - ck) * muk, v = cv + (pv - cv) * muv; pr = cr; pk = ck; pv = cv;
	v_mov_b32_e32 v44, v229
	v_lshlrev_b32_e32 v78, 16, v166

; __device__ __forceinline__ void rwkv_chunk_group(Frame& F, int bc, unsigned long long& tsub) {
;     ...
;         const int gc = h * 64 + ch;
;         const float mur = mu[gc], muk = mu[512 + gc], muv = mu[1024 + gc];
;         const float w0 = (PRM + 2048)[gc], a0 = (PRM + 2560)[gc], k_k = (PRM + 3072)[gc], k_a = (PRM + 3584)[gc], r_k = (PRM + 4096)[gc];
	v_mov_b32_e32 v46, v230


; __device__ __forceinline__ void rwkv_chunk_group(Frame& F, int bc, unsigned long long& tsub) {
;     ...
;         float pr = bf2f(raw[0][0]), pk = bf2f(raw[0][1]), pv = bf2f(raw[0][2]);
;         bf16* VBp = (bf16*)(F.ws + WS_VB) + (size_t)item * 4096; bf16* Gp = (bf16*)(F.ws + WS_G) + (size_t)item * 4096;
;         float run = 0.f; float kkv[8], icv[8], sq[8], bq[8];
; #pragma unroll
;         for (int tt = 0; tt < 8; ++tt) { const int t = tb + tt;
;             const float cr = bf2f(raw[tt + 1][0]), ck = bf2f(raw[tt + 1][1]), cv = bf2f(raw[tt + 1][2]);
;             const float r = cr + (pr - cr) * mur, k = ck + (pk - ck) * muk, v = cv + (pv - cv) * muv; pr = cr; pk = ck; pv = cv;
	v_lshlrev_b32_e32 v86, 16, v157
	v_and_b32_e32 v91, 0xffff0000, v168

; #define LAS __attribute__((address_space(3)))
; __device__ __forceinline__ float sigmoidf_(float x) { return __builtin_amdgcn_rcpf(1.0f + __expf(-x)); }
; __device__ __forceinline__ void rwkv_chunk_group(Frame& F, int bc, unsigned long long& tsub) {
;     ...
;         for (int tt = 0; tt < 8; ++tt) { const int t = tb + tt;
;             const float cr = bf2f(raw[tt + 1][0]), ck = bf2f(raw[tt + 1][1]), cv = bf2f(raw[tt + 1][2]);
;             const float r = cr + (pr - cr) * mur, k = ck + (pk - ck) * muk, v = cv + (pv - cv) * muv; pr = cr; pk = ck; pv = cv;
;             const float wl = *(const LAS float*)(L + L_WL + (t * 65 + ch) * 4), al = *(const LAS float*)(L + L_AL + (t * 65 + ch) * 4), gl = *(const LAS float*)(L + L_GL + (t * 65 + ch) * 4);
;             const float z = -(w0 + wl); const float sp = fmaxf(z, 0.f) + __logf(1.f + __expf(-fabsf(z)));
;             const float lgd = -__expf(-sp - 0.5f);
;             const float ic = sigmoidf_(a0 + al);
;             const float kv = k * k_k; const float kq = k * (1.f + (ic - 1.f) * k_a);
;             kkv[tt] = kv; icv[tt] = ic; sq[tt] = kv * kv; bq[tt] = r * kq * r_k;
;             rr[tt] = r; kp[tt] = kq; vv[tt] = v; run += lgd; ld[tt] = run; ggv[tt] = gl;
;         }
	v_mov_b32_e32 v103, v231
	v_lshlrev_b32_e32 v36, 16, v153
	v_lshlrev_b32_e32 v37, 16, v154
	v_sub_f32_e32 v36, v36, v37
	v_add_u32_e32 v38, s6, v119
	v_add_u32_e32 v39, s7, v119
	ds_read_b32 v38, v38
	ds_read_b32 v47, v39
	ds_read_b32 v177, v41
	ds_read_b32 v185, v87
	ds_read_b32 v191, v191
	v_lshlrev_b32_e32 v90, 16, v168
	v_and_b32_e32 v85, 0xffff0000, v169
	ds_read_b32 v182, v83
	ds_read_b32 v96, v96
	ds_read_b32 v189, v93
	ds_read_b32 v193, v97
	ds_read_b32 v194, v192
	s_waitcnt vmcnt(7)
	v_fma_f32 v173, v36, v95, v37
	v_add_u32_e32 v36, s33, v119
	ds_read_b32 v36, v36
	s_waitcnt vmcnt(4) lgkmcnt(0)
	v_add_f32_e32 v36, v45, v36
	v_max_f32_e64 v39, -v36, 0
	v_mul_f32_e64 v36, |v36|, s1
	v_exp_f32_e32 v36, v36
	s_nop 0
	v_add_f32_e32 v36, 1.0, v36
	v_cmp_gt_f32_e32 vcc, s8, v36
	s_nop 1
	v_cndmask_b32_e64 v40, 0, 32, vcc
	v_ldexp_f32 v36, v36, v40
	v_log_f32_e32 v36, v36
	s_nop 0
	v_mul_f32_e32 v40, 0x3f317217, v36
	v_fma_f32 v40, v36, s9, -v40
	v_fmac_f32_e32 v40, 0x3377d1cf, v36
	v_fmac_f32_e32 v40, 0x3f317217, v36
	v_cmp_lt_f32_e64 s[64:65], |v36|, s10
	s_nop 1
	v_cndmask_b32_e64 v36, v36, v40, s[64:65]
	v_cndmask_b32_e32 v40, 0, v147, vcc
	v_sub_f32_e32 v36, v36, v40
	v_add_f32_e32 v36, v39, v36
	v_add_u32_e32 v39, s33, v120
	ds_read_b32 v39, v39
	v_sub_f32_e32 v36, -0.5, v36
	v_mul_f32_e32 v36, 0x3fb8aa3b, v36
	v_exp_f32_e32 v102, v36
	s_waitcnt vmcnt(3)
	v_add_f32_e32 v36, v43, v38
	v_mul_f32_e32 v36, 0xbfb8aa3b, v36
	v_add_u32_e32 v40, s6, v120
	v_exp_f32_e32 v36, v36
	ds_read_b32 v40, v40
	s_waitcnt lgkmcnt(1)
	v_add_f32_e32 v39, v45, v39
	v_max_f32_e64 v41, -v39, 0
	v_mul_f32_e64 v39, |v39|, s1
	v_exp_f32_e32 v39, v39
	v_add_f32_e32 v36, 1.0, v36
	v_rcp_f32_e32 v38, v36
	v_sub_f32_e32 v36, v37, v82
	v_fma_f32 v174, v36, v95, v82
	v_and_b32_e32 v37, 0xffff0000, v161
	v_lshlrev_b32_e32 v36, 16, v161
	v_add_f32_e32 v39, 1.0, v39
	v_pk_add_f32 v[36:37], v[36:37], v[76:77] neg_lo:[0,1] neg_hi:[0,1]
	v_cmp_gt_f32_e32 vcc, s8, v39
	v_pk_fma_f32 v[36:37], v[36:37], v[52:53], v[76:77] op_sel_hi:[1,0,1]
	s_nop 0
	v_cndmask_b32_e64 v76, 0, 32, vcc
	v_ldexp_f32 v39, v39, v76
	v_log_f32_e32 v39, v39
	s_nop 0
	v_mul_f32_e32 v76, 0x3f317217, v39
	v_fma_f32 v76, v39, s9, -v76
	v_fmac_f32_e32 v76, 0x3377d1cf, v39
	v_fmac_f32_e32 v76, 0x3f317217, v39
	v_cmp_lt_f32_e64 s[64:65], |v39|, s10
	s_nop 1
	v_cndmask_b32_e64 v39, v39, v76, s[64:65]
	v_cndmask_b32_e32 v76, 0, v147, vcc
	v_sub_f32_e32 v39, v39, v76
	v_add_f32_e32 v39, v41, v39
	v_sub_f32_e32 v39, -0.5, v39
	v_mul_f32_e32 v39, 0x3fb8aa3b, v39
	v_exp_f32_e32 v76, v39
	s_waitcnt lgkmcnt(0)
	v_add_f32_e32 v39, v43, v40
	v_mul_f32_e32 v39, 0xbfb8aa3b, v39
	v_exp_f32_e32 v39, v39
	v_and_b32_e32 v41, 0xffff0000, v160
	v_lshlrev_b32_e32 v40, 16, v160
	v_pk_add_f32 v[40:41], v[40:41], v[78:79] neg_lo:[0,1] neg_hi:[0,1]
	v_add_f32_e32 v39, 1.0, v39
	v_rcp_f32_e32 v39, v39
	v_pk_fma_f32 v[80:81], v[40:41], v[42:43], v[78:79] op_sel_hi:[1,0,1]
	v_sub_f32_e64 v176, -v102, v76
	v_lshlrev_b32_e32 v76, 16, v156
	v_pk_add_f32 v[40:41], v[38:39], -1.0 op_sel_hi:[1,0]
	s_waitcnt vmcnt(1)
	v_pk_fma_f32 v[40:41], v[46:47], v[40:41], 1.0 op_sel_hi:[0,1,0]
	v_pk_mul_f32 v[40:41], v[80:81], v[40:41]
	s_nop 0
	v_mul_f32_e32 v78, v173, v40
	s_waitcnt vmcnt(0)
	v_mul_f32_e32 v101, v103, v78
	v_mul_f32_e32 v78, v174, v41
	v_mul_f32_e32 v100, v103, v78
	v_sub_f32_e32 v78, v82, v76
	v_fma_f32 v175, v78, v95, v76
	v_add_u32_e32 v78, s33, v121
	ds_read_b32 v78, v78
	v_add_u32_e32 v82, s6, v121
	ds_read_b32 v82, v82
	v_sub_f32_e32 v76, v76, v86
	v_fma_f32 v178, v76, v95, v86
	s_waitcnt lgkmcnt(1)
	v_add_f32_e32 v78, v45, v78
	v_max_f32_e64 v83, -v78, 0
	v_mul_f32_e64 v78, |v78|, s1
	v_exp_f32_e32 v78, v78
	s_waitcnt lgkmcnt(0)
	v_add_f32_e32 v82, v43, v82
	v_mul_f32_e32 v82, 0xbfb8aa3b, v82
	v_exp_f32_e32 v82, v82
	v_add_f32_e32 v78, 1.0, v78
	v_cmp_gt_f32_e32 vcc, s8, v78
	v_add_f32_e32 v82, 1.0, v82
	s_nop 0
	v_cndmask_b32_e64 v84, 0, 32, vcc
	v_ldexp_f32 v78, v78, v84
	v_log_f32_e32 v78, v78
	v_rcp_f32_e32 v82, v82
	v_mul_f32_e32 v84, 0x3f317217, v78
	v_fma_f32 v84, v78, s9, -v84
	v_fmac_f32_e32 v84, 0x3377d1cf, v78
	v_fmac_f32_e32 v84, 0x3f317217, v78
	v_cmp_lt_f32_e64 s[64:65], |v78|, s10
	s_nop 1
	v_cndmask_b32_e64 v78, v78, v84, s[64:65]
	v_cndmask_b32_e32 v84, 0, v147, vcc
	v_sub_f32_e32 v78, v78, v84
	v_add_f32_e32 v78, v83, v78
	v_sub_f32_e32 v78, -0.5, v78
	v_mul_f32_e32 v78, 0x3fb8aa3b, v78
	v_exp_f32_e32 v78, v78
	v_add_u32_e32 v83, s6, v122
	ds_read_b32 v83, v83
	v_lshlrev_b32_e32 v84, 16, v169
	v_sub_f32_e32 v179, v176, v78
	v_add_u32_e32 v78, s33, v122
	ds_read_b32 v78, v78
	v_pk_mov_b32 v[76:77], v[76:77], v[84:85] op_sel:[1,0]
	s_waitcnt lgkmcnt(0)
	v_add_f32_e32 v78, v45, v78
	v_max_f32_e64 v87, -v78, 0
	v_mul_f32_e64 v78, |v78|, s1
	v_exp_f32_e32 v78, v78
	v_pk_add_f32 v[76:77], v[76:77], v[84:85] neg_lo:[0,1] neg_hi:[0,1]
	v_add_f32_e32 v78, 1.0, v78
	v_cmp_gt_f32_e32 vcc, s8, v78
	v_pk_fma_f32 v[76:77], v[76:77], v[52:53], v[84:85] op_sel_hi:[1,0,1]
	s_nop 0
	v_cndmask_b32_e64 v88, 0, 32, vcc
	v_ldexp_f32 v78, v78, v88
	v_log_f32_e32 v78, v78
	s_nop 0
	v_mul_f32_e32 v88, 0x3f317217, v78
	v_fma_f32 v88, v78, s9, -v88
	v_fmac_f32_e32 v88, 0x3377d1cf, v78
	v_fmac_f32_e32 v88, 0x3f317217, v78
	v_cmp_lt_f32_e64 s[64:65], |v78|, s10
	s_nop 1
	v_cndmask_b32_e64 v78, v78, v88, s[64:65]
	v_cndmask_b32_e32 v88, 0, v147, vcc
	v_sub_f32_e32 v78, v78, v88
	v_add_f32_e32 v78, v87, v78
	v_sub_f32_e32 v78, -0.5, v78
	v_mul_f32_e32 v78, 0x3fb8aa3b, v78
	v_exp_f32_e32 v87, v78
	v_add_f32_e32 v78, v43, v83
	v_mul_f32_e32 v78, 0xbfb8aa3b, v78
	v_exp_f32_e32 v78, v78
	v_sub_f32_e32 v181, v179, v87
	v_lshlrev_b32_e32 v87, 16, v158
	v_sub_f32_e32 v86, v86, v87
	v_add_f32_e32 v78, 1.0, v78
	v_rcp_f32_e32 v83, v78
	v_pk_mov_b32 v[78:79], v[78:79], v[90:91] op_sel:[1,0]
	v_fma_f32 v180, v86, v95, v87
	v_pk_add_f32 v[78:79], v[78:79], v[90:91] neg_lo:[0,1] neg_hi:[0,1]
	v_add_u32_e32 v86, s33, v123
	v_pk_fma_f32 v[88:89], v[78:79], v[42:43], v[90:91] op_sel_hi:[1,0,1]
	v_pk_add_f32 v[78:79], v[82:83], -1.0 op_sel_hi:[1,0]
	ds_read_b32 v86, v86
	v_pk_fma_f32 v[78:79], v[46:47], v[78:79], 1.0 op_sel_hi:[0,1,0]
	v_pk_mul_f32 v[78:79], v[88:89], v[78:79]
	s_nop 0
	v_mul_f32_e32 v92, v175, v78
	v_mul_f32_e32 v187, v103, v92
	v_mul_f32_e32 v92, v178, v79
	v_mul_f32_e32 v186, v103, v92
	v_add_u32_e32 v92, s6, v123
	ds_read_b32 v92, v92
	s_waitcnt lgkmcnt(1)
; #define LAS __attribute__((address_space(3)))
; __device__ __forceinline__ float sigmoidf_(float x) { return __builtin_amdgcn_rcpf(1.0f + __expf(-x)); }
; __device__ __forceinline__ void rwkv_chunk_group(Frame& F, int bc, unsigned long long& tsub) {
;     ...
;         for (int tt = 0; tt < 8; ++tt) { const int t = tb + tt;
;             const float cr = bf2f(raw[tt + 1][0]), ck = bf2f(raw[tt + 1][1]), cv = bf2f(raw[tt + 1][2]);
;             const float r = cr + (pr - cr) * mur, k = ck + (pk - ck) * muk, v = cv + (pv - cv) * muv; pr = cr; pk = ck; pv = cv;
;             const float wl = *(const LAS float*)(L + L_WL + (t * 65 + ch) * 4), al = *(const LAS float*)(L + L_AL + (t * 65 + ch) * 4), gl = *(const LAS float*)(L + L_GL + (t * 65 + ch) * 4);
;             const float z = -(w0 + wl); const float sp = fmaxf(z, 0.f) + __logf(1.f + __expf(-fabsf(z)));
;             const float lgd = -__expf(-sp - 0.5f);
;             const float ic = sigmoidf_(a0 + al);
;             const float kv = k * k_k; const float kq = k * (1.f + (ic - 1.f) * k_a);
;             kkv[tt] = kv; icv[tt] = ic; sq[tt] = kv * kv; bq[tt] = r * kq * r_k;
;             rr[tt] = r; kp[tt] = kq; vv[tt] = v; run += lgd; ld[tt] = run; ggv[tt] = gl;
;         }
	v_add_f32_e32 v86, v45, v86
	v_max_f32_e64 v93, -v86, 0
	v_mul_f32_e64 v86, |v86|, s1
	v_exp_f32_e32 v86, v86
	s_nop 0
	v_add_f32_e32 v86, 1.0, v86
	v_cmp_gt_f32_e32 vcc, s8, v86
	s_nop 1
	v_cndmask_b32_e64 v94, 0, 32, vcc
	v_ldexp_f32 v86, v86, v94
	v_log_f32_e32 v86, v86
	s_nop 0
	v_mul_f32_e32 v94, 0x3f317217, v86
	v_fma_f32 v94, v86, s9, -v94
	v_fmac_f32_e32 v94, 0x3377d1cf, v86
	v_fmac_f32_e32 v94, 0x3f317217, v86
	v_cmp_lt_f32_e64 s[64:65], |v86|, s10
	s_nop 1
	v_cndmask_b32_e64 v86, v86, v94, s[64:65]
	v_cndmask_b32_e32 v94, 0, v147, vcc
	v_sub_f32_e32 v86, v86, v94
	v_lshlrev_b32_e32 v94, 16, v159
	v_sub_f32_e32 v87, v87, v94
	v_fma_f32 v183, v87, v95, v94
	v_add_u32_e32 v87, s33, v124
	ds_read_b32 v87, v87
	v_add_f32_e32 v86, v93, v86
	v_sub_f32_e32 v86, -0.5, v86
	v_mul_f32_e32 v86, 0x3fb8aa3b, v86
	v_exp_f32_e32 v93, v86
	s_waitcnt lgkmcnt(0)
	v_add_f32_e32 v87, v45, v87
	v_max_f32_e64 v97, -v87, 0
	v_mul_f32_e64 v87, |v87|, s1
	v_exp_f32_e32 v87, v87
	v_add_f32_e32 v86, v43, v92
	v_mul_f32_e32 v86, 0xbfb8aa3b, v86
	v_exp_f32_e32 v86, v86
	v_add_f32_e32 v87, 1.0, v87
	v_cmp_gt_f32_e32 vcc, s8, v87
	v_sub_f32_e32 v184, v181, v93
	v_add_f32_e32 v86, 1.0, v86
	v_cndmask_b32_e64 v98, 0, 32, vcc
	v_ldexp_f32 v87, v87, v98
	v_log_f32_e32 v87, v87
	v_rcp_f32_e32 v86, v86
	v_sub_f32_e32 v94, v94, v197
	v_and_b32_e32 v93, 0xffff0000, v171
	v_mul_f32_e32 v98, 0x3f317217, v87
	v_fma_f32 v98, v87, s9, -v98
	v_fmac_f32_e32 v98, 0x3377d1cf, v87
	v_fmac_f32_e32 v98, 0x3f317217, v87
	v_cmp_lt_f32_e64 s[64:65], |v87|, s10
	v_lshlrev_b32_e32 v92, 16, v171
	v_pk_mov_b32 v[84:85], v[84:85], v[92:93] op_sel:[1,0]
	v_cndmask_b32_e64 v87, v87, v98, s[64:65]
	v_cndmask_b32_e32 v98, 0, v147, vcc
	v_sub_f32_e32 v87, v87, v98
	v_add_f32_e32 v87, v97, v87
	v_sub_f32_e32 v87, -0.5, v87
	v_mul_f32_e32 v87, 0x3fb8aa3b, v87
	v_exp_f32_e32 v188, v87
	v_add_f32_e32 v87, v43, v96
	v_mul_f32_e32 v87, 0xbfb8aa3b, v87
	v_exp_f32_e32 v87, v87
	v_and_b32_e32 v97, 0xffff0000, v170
	v_lshlrev_b32_e32 v96, 16, v170
	v_pk_mov_b32 v[90:91], v[90:91], v[96:97] op_sel:[1,0]
	v_add_f32_e32 v87, 1.0, v87
	v_rcp_f32_e32 v87, v87
	v_pk_add_f32 v[90:91], v[90:91], v[96:97] neg_lo:[0,1] neg_hi:[0,1]
	v_pk_add_f32 v[84:85], v[84:85], v[92:93] neg_lo:[0,1] neg_hi:[0,1]
	v_pk_fma_f32 v[98:99], v[90:91], v[42:43], v[96:97] op_sel_hi:[1,0,1]
	v_pk_add_f32 v[90:91], v[86:87], -1.0 op_sel_hi:[1,0]
	v_pk_fma_f32 v[84:85], v[84:85], v[52:53], v[92:93] op_sel_hi:[1,0,1]
	v_pk_fma_f32 v[90:91], v[46:47], v[90:91], 1.0 op_sel_hi:[0,1,0]
	v_pk_mul_f32 v[90:91], v[98:99], v[90:91]
	s_nop 0
	v_mul_f32_e32 v190, v180, v90
	v_mul_f32_e32 v196, v103, v190
	v_mul_f32_e32 v190, v183, v91
	v_mul_f32_e32 v195, v103, v190
	v_sub_f32_e32 v190, v184, v188
	v_fma_f32 v188, v94, v95, v197
	v_add_u32_e32 v94, s33, v125
	ds_read_b32 v94, v94
	v_permlane32_swap_b32_e32 v101, v196
	v_permlane32_swap_b32_e32 v100, v195
	s_waitcnt lgkmcnt(0)
	v_add_f32_e32 v94, v45, v94
	v_max_f32_e64 v192, -v94, 0
	v_mul_f32_e64 v94, |v94|, s1
	v_exp_f32_e32 v94, v94
	v_add_f32_e32 v201, v101, v196
	v_add_f32_e32 v195, v100, v195
	v_add_f32_e32 v94, 1.0, v94
	v_cmp_gt_f32_e32 vcc, s8, v94
	s_nop 1
	v_cndmask_b32_e64 v198, 0, 32, vcc
	v_ldexp_f32 v94, v94, v198
	v_log_f32_e32 v94, v94
	s_nop 0
	v_mul_f32_e32 v198, 0x3f317217, v94
	v_fma_f32 v198, v94, s9, -v198
	v_fmac_f32_e32 v198, 0x3377d1cf, v94
	v_fmac_f32_e32 v198, 0x3f317217, v94
	v_cmp_lt_f32_e64 s[64:65], |v94|, s10
	s_nop 1
	v_cndmask_b32_e64 v94, v94, v198, s[64:65]
	v_cndmask_b32_e32 v198, 0, v147, vcc
	v_sub_f32_e32 v94, v94, v198
	v_lshlrev_b32_e32 v198, 16, v172
	v_pk_mov_b32 v[92:93], v[92:93], v[198:199] op_sel:[1,0]
	v_add_f32_e32 v94, v192, v94
	v_pk_add_f32 v[92:93], v[92:93], v[198:199] neg_lo:[0,1] neg_hi:[0,1]
	v_sub_f32_e32 v94, -0.5, v94
	v_pk_fma_f32 v[92:93], v[92:93], v[52:53], v[198:199] op_sel_hi:[1,0,1]
	v_add_u32_e32 v52, s33, v126
	ds_read_b32 v52, v52
	v_mul_f32_e32 v94, 0x3fb8aa3b, v94
	v_exp_f32_e32 v192, v94
	v_add_f32_e32 v94, v43, v191
	v_lshlrev_b32_e32 v191, 16, v163
	v_sub_f32_e32 v197, v197, v191
	v_fmac_f32_e32 v191, v197, v95
	v_add_u32_e32 v95, s6, v126
	v_add_u32_e32 v197, s7, v126
	ds_read_b32 v95, v95
	ds_read_b32 v200, v197
	s_waitcnt lgkmcnt(2)
	v_add_f32_e32 v45, v45, v52
	v_max_f32_e64 v52, -v45, 0
	v_mul_f32_e64 v45, |v45|, s1
	v_exp_f32_e32 v45, v45
	s_waitcnt lgkmcnt(1)
; #define GAS __attribute__((address_space(1)))
; __device__ __forceinline__ void wave_sum8(float (&x)[8]) {
;     const float y0 = swap32_add(x[0], x[4]), y1 = swap32_add(x[1], x[5]), y2 = swap32_add(x[2], x[6]), y3 = swap32_add(x[3], x[7]);
;     float z0 = swap16_add(y0, y2), z1 = swap16_add(y1, y3);
;     z0 = dpp_add(z0, 0); z1 = dpp_add(z1, 0); z0 = dpp_add(z0, 1); z1 = dpp_add(z1, 1); z0 = dpp_add(z0, 2); z1 = dpp_add(z1, 2); z0 = dpp_add(z0, 3); z1 = dpp_add(z1, 3);
;     const int i0 = __builtin_bit_cast(int, z0), i1 = __builtin_bit_cast(int, z1);
;     x[0] = __builtin_bit_cast(float, __builtin_amdgcn_readlane(i0, 0));  x[2] = __builtin_bit_cast(float, __builtin_amdgcn_readlane(i0, 16));
;     x[4] = __builtin_bit_cast(float, __builtin_amdgcn_readlane(i0, 32)); x[6] = __builtin_bit_cast(float, __builtin_amdgcn_readlane(i0, 48));
; __device__ __forceinline__ void rwkv_chunk_group(Frame& F, int bc, unsigned long long& tsub) {
;     ...
;             const float z = -(w0 + wl); const float sp = fmaxf(z, 0.f) + __logf(1.f + __expf(-fabsf(z)));
;             const float lgd = -__expf(-sp - 0.5f);
;             const float ic = sigmoidf_(a0 + al);
;             const float kv = k * k_k; const float kq = k * (1.f + (ic - 1.f) * k_a);
;             kkv[tt] = kv; icv[tt] = ic; sq[tt] = kv * kv; bq[tt] = r * kq * r_k;
;             rr[tt] = r; kp[tt] = kq; vv[tt] = v; run += lgd; ld[tt] = run; ggv[tt] = gl;
;         }
;         wave_sum8(sq); wave_sum8(bq);
; #pragma unroll
;         for (int tt = 0; tt < 8; ++tt) { const float kn = kkv[tt] * __builtin_amdgcn_rsqf(fmaxf(sq[tt], 1e-24f));
;             aa[tt] = -kn; bb[tt] = kn * icv[tt]; vbv[tt] = bq[tt] * vv[tt]; }
;         *(LAS float*)(L + L_GT + (w * 64 + ch) * 4) = run;
;         *(GAS v4u*)(VBp + ch * 64 + tb) = (v4u){pk2(vbv[0], vbv[1]), pk2(vbv[2], vbv[3]), pk2(vbv[4], vbv[5]), pk2(vbv[6], vbv[7])};
;         *(GAS v4u*)(Gp + ch * 64 + tb) = (v4u){pk2(ggv[0], ggv[1]), pk2(ggv[2], ggv[3]), pk2(ggv[4], ggv[5]), pk2(ggv[6], ggv[7])};
;         if (hh + 1 < RW_H) {
;             const bool has = (c * CH + tb > 0);
; #pragma unroll
;             for (int tt = 0; tt < 9; ++tt) { const size_t off = (size_t)(row0 + tb + tt - 1) * PRW + hnext * 64 + ch;
;                 if (tt > 0 || has) { raw[tt][0] = P[off]; raw[tt][1] = P[off + 512]; raw[tt][2] = P[off + 1024]; } }
	v_add_f32_e32 v43, v43, v95
	v_mul_f32_e32 v94, 0xbfb8aa3b, v94
	v_mul_f32_e32 v43, 0xbfb8aa3b, v43
	v_add_f32_e32 v45, 1.0, v45
	v_cmp_gt_f32_e32 vcc, s8, v45
	v_exp_f32_e32 v94, v94
	v_exp_f32_e32 v43, v43
	v_cndmask_b32_e64 v197, 0, 32, vcc
	v_ldexp_f32 v45, v45, v197
	v_log_f32_e32 v45, v45
	v_add_f32_e32 v94, 1.0, v94
	v_add_f32_e32 v43, 1.0, v43
	v_rcp_f32_e32 v94, v94
	v_mul_f32_e32 v197, 0x3f317217, v45
	v_fma_f32 v197, v45, s9, -v197
	v_fmac_f32_e32 v197, 0x3377d1cf, v45
	v_fmac_f32_e32 v197, 0x3f317217, v45
	v_cmp_lt_f32_e64 s[64:65], |v45|, s10
	v_rcp_f32_e32 v95, v43
	v_sub_f32_e32 v192, v190, v192
	v_cndmask_b32_e64 v45, v45, v197, s[64:65]
	v_cndmask_b32_e32 v197, 0, v147, vcc
	v_sub_f32_e32 v45, v45, v197
	v_add_f32_e32 v45, v52, v45
	v_sub_f32_e32 v45, -0.5, v45
	v_mul_f32_e32 v45, 0x3fb8aa3b, v45
	v_exp_f32_e32 v45, v45
	s_nop 0
	v_pk_mul_f32 v[100:101], v[80:81], v[44:45] op_sel_hi:[1,0]
	v_pk_mul_f32 v[80:81], v[98:99], v[44:45] op_sel_hi:[1,0]
	v_pk_mul_f32 v[196:197], v[100:101], v[100:101]
	v_pk_mul_f32 v[98:99], v[80:81], v[80:81]
	v_sub_f32_e32 v52, v192, v45
	s_nop 0
	v_permlane32_swap_b32_e32 v196, v98
	v_permlane32_swap_b32_e32 v197, v99
	v_add_f32_e32 v196, v196, v98
	v_add_f32_e32 v197, v197, v99
	v_lshlrev_b32_e32 v98, 16, v165
	v_and_b32_e32 v99, 0xffff0000, v165
	v_pk_mov_b32 v[96:97], v[96:97], v[98:99] op_sel:[1,0]
	v_pk_mul_f32 v[88:89], v[88:89], v[44:45] op_sel_hi:[1,0]
	v_pk_add_f32 v[96:97], v[96:97], v[98:99] neg_lo:[0,1] neg_hi:[0,1]
	v_pk_mul_f32 v[198:199], v[88:89], v[88:89]
	v_pk_fma_f32 v[42:43], v[96:97], v[42:43], v[98:99] op_sel_hi:[1,0,1]
	v_pk_add_f32 v[98:99], v[94:95], -1.0 op_sel_hi:[1,0]
	v_pk_mul_f32 v[44:45], v[42:43], v[44:45] op_sel_hi:[1,0]
	v_pk_fma_f32 v[98:99], v[46:47], v[98:99], 1.0 op_sel_hi:[0,1,0]
	v_pk_mul_f32 v[42:43], v[42:43], v[98:99]
	v_pk_mul_f32 v[96:97], v[44:45], v[44:45]
	v_mul_f32_e32 v46, v188, v42
	v_mul_f32_e32 v46, v103, v46
	s_nop 1
	v_permlane32_swap_b32_e32 v187, v46
	v_add_f32_e32 v46, v187, v46
	v_mul_f32_e32 v98, v191, v43
	s_nop 0
	v_permlane16_swap_b32_e32 v201, v46
	v_mul_f32_e32 v98, v103, v98
	v_add_f32_e32 v46, v201, v46
	s_nop 0
	v_permlane32_swap_b32_e32 v186, v98
	v_add_f32_dpp v46, v46, v46 quad_perm:[1,0,3,2] row_mask:0xf bank_mask:0xf bound_ctrl:1
	v_add_f32_e32 v98, v186, v98
	s_nop 1
	v_permlane16_swap_b32_e32 v195, v98
	v_add_f32_dpp v46, v46, v46 quad_perm:[2,3,0,1] row_mask:0xf bank_mask:0xf bound_ctrl:1
	v_add_f32_e32 v98, v195, v98
	v_permlane32_swap_b32_e32 v198, v96
	v_add_f32_dpp v46, v46, v46 row_half_mirror row_mask:0xf bank_mask:0xf bound_ctrl:1
	v_permlane32_swap_b32_e32 v199, v97
	s_nop 0
	v_add_f32_dpp v46, v46, v46 row_mirror row_mask:0xf bank_mask:0xf bound_ctrl:1
	v_add_f32_dpp v98, v98, v98 quad_perm:[1,0,3,2] row_mask:0xf bank_mask:0xf bound_ctrl:1
	v_readlane_b32 s14, v46, 0
	v_readlane_b32 s64, v46, 16
	v_readlane_b32 s72, v46, 32
	v_readlane_b32 s96, v46, 48
	v_add_f32_e32 v46, v198, v96
	v_add_f32_e32 v96, v199, v97
	v_add_f32_dpp v98, v98, v98 quad_perm:[2,3,0,1] row_mask:0xf bank_mask:0xf bound_ctrl:1
	v_permlane16_swap_b32_e32 v196, v46
	v_permlane16_swap_b32_e32 v197, v96
	v_add_f32_dpp v98, v98, v98 row_half_mirror row_mask:0xf bank_mask:0xf bound_ctrl:1
	v_add_f32_e32 v46, v196, v46
	v_add_f32_e32 v96, v197, v96
	v_add_f32_dpp v98, v98, v98 row_mirror row_mask:0xf bank_mask:0xf bound_ctrl:1
	v_add_f32_dpp v46, v46, v46 quad_perm:[1,0,3,2] row_mask:0xf bank_mask:0xf bound_ctrl:1
	v_add_f32_dpp v96, v96, v96 quad_perm:[1,0,3,2] row_mask:0xf bank_mask:0xf bound_ctrl:1
	v_readlane_b32 s73, v98, 32
	v_add_f32_dpp v46, v46, v46 quad_perm:[2,3,0,1] row_mask:0xf bank_mask:0xf bound_ctrl:1
	v_add_f32_dpp v96, v96, v96 quad_perm:[2,3,0,1] row_mask:0xf bank_mask:0xf bound_ctrl:1
	v_readlane_b32 s15, v98, 0
	v_readlane_b32 s65, v98, 16
	v_readlane_b32 s97, v98, 48
	v_add_f32_dpp v46, v46, v46 row_half_mirror row_mask:0xf bank_mask:0xf bound_ctrl:1
	v_add_f32_dpp v96, v96, v96 row_half_mirror row_mask:0xf bank_mask:0xf bound_ctrl:1
	v_pk_mul_f32 v[196:197], v[84:85], s[72:73]
	s_lshl_b64 s[72:73], s[66:67], 13
	v_pk_mul_f32 v[98:99], v[36:37], s[14:15]
	v_pk_mul_f32 v[186:187], v[76:77], s[64:65]
	v_add_f32_dpp v46, v46, v46 row_mirror row_mask:0xf bank_mask:0xf bound_ctrl:1
	v_add_f32_dpp v96, v96, v96 row_mirror row_mask:0xf bank_mask:0xf bound_ctrl:1
	v_pk_mul_f32 v[198:199], v[92:93], s[96:97]
	v_readlane_b32 s15, v254, 39
	s_cmp_eq_u32 s68, 7
	v_readlane_b32 s93, v46, 0
	v_readlane_b32 s71, v46, 16
	v_readlane_b32 s69, v46, 32
	v_readlane_b32 s64, v46, 48
	v_readlane_b32 s14, v96, 0
	v_readlane_b32 s77, v96, 16
	v_readlane_b32 s70, v96, 32
	v_readlane_b32 s65, v96, 48
	v_add_u32_e32 v46, s15, v105
	v_cvt_pk_bf16_f32 v96, v98, v99
	v_cvt_pk_bf16_f32 v97, v186, v187
	v_cvt_pk_bf16_f32 v98, v196, v197
	v_cvt_pk_bf16_f32 v99, v198, v199
	v_lshl_add_u64 v[186:187], v[62:63], 0, s[72:73]
	s_cselect_b64 s[96:97], -1, 0
	ds_write_b32 v46, v52
	global_store_dwordx4 v[186:187], v[96:99], off
	s_and_b64 vcc, exec, s[96:97]
	s_nop 0
	v_cvt_pk_bf16_f32 v96, v47, v177
	v_cvt_pk_bf16_f32 v97, v182, v185
	v_cvt_pk_bf16_f32 v98, v189, v193
	s_waitcnt lgkmcnt(1)
	v_cvt_pk_bf16_f32 v99, v194, v200
	v_lshl_add_u64 v[46:47], v[64:65], 0, s[72:73]
	global_store_dwordx4 v[46:47], v[96:99], off
	s_cbranch_vccnz .LBB0_1416
	v_readlane_b32 s72, v254, 60
	s_lshl_b32 s94, s13, 7
	v_readlane_b32 s73, v254, 61
	v_lshl_add_u64 v[46:47], v[56:57], 0, s[94:95]
	s_andn2_b64 vcc, exec, s[72:73]
	s_cbranch_vccnz .LBB0_1415
	v_readlane_b32 s72, v254, 62
	v_readlane_b32 s73, v254, 63
	s_nop 1
	v_lshl_add_u64 v[96:97], v[46:47], 0, s[72:73]
	global_load_ushort v153, v[96:97], off
	global_load_ushort v202, v[96:97], off offset:1024
	global_load_ushort v215, v[96:97], off offset:2048

; #define LAS __attribute__((address_space(3)))
; __device__ __forceinline__ void rwkv_chunk_group(Frame& F, int bc, unsigned long long& tsub) {
;     ...
;         float offs = 0.f, tot = 0.f;
; #pragma unroll
;         for (int g = 0; g < 8; ++g) { const float x = *(const LAS float*)(L + L_GT + (g * 64 + ch) * 4); if (g < w) offs += x; tot += x; }
.LBB0_1418:
	v_cndmask_b32_e64 v182, v185, 0, s[82:83]
	v_readlane_b32 s66, v254, 40
	v_add_f32_e32 v47, v47, v182
	v_readlane_b32 s67, v254, 41

; #define LAS __attribute__((address_space(3)))
; __device__ __forceinline__ unsigned pk2(float lo, float hi) { f32x2_k v = {lo, hi}; bf16x2_k b = __builtin_convertvector(v, bf16x2_k); return __builtin_bit_cast(unsigned, b); }
; __device__ __forceinline__ unsigned f2bf(float f) { return pk2(f, 0.f) & 0xffffu; }
; __device__ __forceinline__ void rwkv_chunk_group(Frame& F, int bc, unsigned long long& tsub) {
;     ...
;         float offs = 0.f, tot = 0.f;
; #pragma unroll
;         for (int g = 0; g < 8; ++g) { const float x = *(const LAS float*)(L + L_GT + (g * 64 + ch) * 4); if (g < w) offs += x; tot += x; }
;         const float etot = __expf(tot);
;         if (w == 0) *(LAS float*)(L + L_WC + ch * 4) = etot;
;         unsigned patt[4], pvt[4], pbh[4], pkh[4]; float hAt = 0.f, hBh = 0.f, hKh = 0.f;
;         float e_ex = __expf(offs);
; #pragma unroll
;         for (int tt = 0; tt < 8; ++tt) { const int t = tb + tt; const float cl = offs + ld[tt];
;             const float e_in = __expf(cl), e_inv = __builtin_amdgcn_rcpf(e_in), e_hat = etot * e_inv;
;             const float At = aa[tt] * e_ex, Bt = bb[tt] * e_inv, Kt = kp[tt] * e_inv, Rt = rr[tt] * e_in, Bh = bb[tt] * e_hat, Kh = kp[tt] * e_hat; e_ex = e_in;
;             *(LAS bf16*)(L + L_AT + t * LD + ch * 2) = (bf16)f2bf(At); *(LAS bf16*)(L + L_BT + t * LD + ch * 2) = (bf16)f2bf(Bt);
;             *(LAS bf16*)(L + L_KT + t * LD + ch * 2) = (bf16)f2bf(Kt); *(LAS bf16*)(L + L_RT + t * LD + ch * 2) = (bf16)f2bf(Rt);
;             if (tt & 1) { patt[tt >> 1] = pk2(hAt, At); pvt[tt >> 1] = pk2(vv[tt - 1], vv[tt]); pbh[tt >> 1] = pk2(hBh, Bh); pkh[tt >> 1] = pk2(hKh, Kh); }
;             hAt = At; hBh = Bh; hKh = Kh;
;         }
	s_mov_b32 s17, s16
	v_cndmask_b32_e64 v47, v182, v47, s[66:67]
	v_readlane_b32 s66, v254, 42
	v_add_f32_e32 v102, v102, v47
	v_readlane_b32 s67, v254, 43
	s_nop 1
	v_cndmask_b32_e64 v47, v47, v102, s[66:67]
	v_readlane_b32 s66, v254, 44
	v_add_f32_e32 v102, v103, v47
	v_readlane_b32 s67, v254, 45
	s_nop 1
	v_cndmask_b32_e64 v47, v47, v102, s[66:67]
	v_readlane_b32 s66, v254, 46
	v_add_f32_e32 v98, v98, v47
	v_readlane_b32 s67, v254, 47
	s_nop 1
	v_cndmask_b32_e64 v47, v47, v98, s[66:67]
	v_readlane_b32 s66, v254, 48
	v_add_f32_e32 v98, v99, v47
	v_readlane_b32 s67, v254, 49
	v_max_f32_e64 v99, s77, s77
	v_max_f32_e32 v99, 0x179abe15, v99
	v_cndmask_b32_e64 v47, v47, v98, s[66:67]
	v_readlane_b32 s66, v254, 50
	v_max_f32_e64 v98, s71, s71
	v_add_f32_e32 v96, v96, v47
	v_readlane_b32 s67, v254, 51
	v_max_f32_e32 v98, 0x179abe15, v98
	v_rsq_f32_e32 v98, v98
	v_cndmask_b32_e64 v47, v47, v96, s[66:67]
	v_rsq_f32_e32 v99, v99
	v_add_f32_e32 v102, v97, v47
	v_max_f32_e64 v97, s14, s14
	v_readlane_b32 s14, v254, 53
	v_readlane_b32 s15, v254, 54
	v_pk_mul_f32 v[88:89], v[88:89], v[98:99]
	v_max_f32_e64 v98, s69, s69
	v_cndmask_b32_e64 v47, v47, v102, s[14:15]
	v_max_f32_e64 v99, s70, s70
	v_add_f32_e32 v102, v177, v47
	v_max_f32_e32 v98, 0x179abe15, v98
	v_max_f32_e32 v99, 0x179abe15, v99
	v_mul_f32_e32 v102, 0x3fb8aa3b, v102
	v_max_f32_e64 v96, s93, s93
	v_rsq_f32_e32 v98, v98
	v_rsq_f32_e32 v99, v99
	v_exp_f32_e32 v103, v102
	v_max_f32_e32 v96, 0x179abe15, v96
	v_max_f32_e32 v97, 0x179abe15, v97
	v_rsq_f32_e32 v96, v96
	v_rsq_f32_e32 v97, v97
	v_pk_mul_f32 v[98:99], v[80:81], v[98:99]
	v_rcp_f32_e32 v80, v103
	v_mul_f32_e32 v81, 0x3fb8aa3b, v47
	v_pk_mul_f32 v[96:97], v[100:101], v[96:97]
	v_exp_f32_e32 v102, v81
	v_pk_mul_f32 v[38:39], v[38:39], v[96:97]
	s_mul_i32 s14, s16, 0x480
	v_mul_f32_e32 v81, v38, v80
	v_pk_mul_f32 v[186:187], v[86:87], v[98:99]
	v_mul_f32_e32 v86, v40, v80
	v_mul_f32_e32 v87, v173, v103
	v_cvt_pk_bf16_f32 v81, v81, s0
	v_add_u32_e32 v173, s14, v58
	ds_write_b16 v173, v81 offset:9216
	v_cvt_pk_bf16_f32 v81, v86, s0
	v_add_f32_e32 v86, v176, v47
	v_mul_f32_e32 v86, 0x3fb8aa3b, v86
	v_max_f32_e64 v100, s64, s64
	v_max_f32_e64 v101, s65, s65
	v_exp_f32_e32 v176, v86
	v_max_f32_e32 v100, 0x179abe15, v100
	v_max_f32_e32 v101, 0x179abe15, v101
	v_rsq_f32_e32 v100, v100
	v_rsq_f32_e32 v101, v101
	ds_write_b16 v173, v81 offset:18432
	v_cvt_pk_bf16_f32 v81, v87, s0
	ds_write_b16 v173, v81 offset:27648
	v_rcp_f32_e32 v81, v176
	v_pk_mul_f32 v[44:45], v[44:45], v[100:101]
	v_pk_mul_f32 v[86:87], v[102:103], v[96:97] neg_lo:[0,1] neg_hi:[0,1]
	v_pk_mul_f32 v[100:101], v[94:95], v[44:45]
	v_cvt_pk_bf16_f32 v94, v86, s0
	ds_write_b16 v173, v94
	v_mul_f32_e32 v94, v39, v81
	v_mul_f32_e32 v95, v41, v81
	v_cvt_pk_bf16_f32 v94, v94, s0
	v_mul_f32_e32 v96, v174, v176
	ds_write_b16 v173, v94 offset:9360
	v_cvt_pk_bf16_f32 v94, v95, s0
	ds_write_b16 v173, v94 offset:18576
	v_cvt_pk_bf16_f32 v94, v96, s0
	ds_write_b16 v173, v94 offset:27792
	v_add_f32_e32 v94, v179, v47
	v_mul_f32_e32 v94, 0x3fb8aa3b, v94
	v_exp_f32_e32 v177, v94
	v_pk_mul_f32 v[82:83], v[82:83], v[88:89]
	v_pk_mul_f32 v[80:81], v[46:47], v[80:81] op_sel_hi:[0,1]
	v_pk_mul_f32 v[40:41], v[40:41], v[80:81]
	v_rcp_f32_e32 v96, v177
	v_pk_mul_f32 v[94:95], v[38:39], v[80:81]
	v_cvt_pk_bf16_f32 v80, v36, v37
	v_cvt_pk_bf16_f32 v97, v87, s0
	v_mul_f32_e32 v36, v82, v96
	v_cvt_pk_bf16_f32 v36, v36, s0
	ds_write_b16 v173, v36 offset:9504
	v_add_f32_e32 v36, v181, v47
	v_mul_f32_e32 v36, 0x3fb8aa3b, v36
	v_exp_f32_e32 v36, v36
	ds_write_b16 v173, v97 offset:144
	v_mul_f32_e32 v37, v78, v96
	v_mul_f32_e32 v39, v175, v177
	v_rcp_f32_e32 v97, v36
	v_cvt_pk_bf16_f32 v37, v37, s0
	v_cvt_pk_bf16_f32 v38, v86, v87
	v_cvt_pk_bf16_f32 v86, v94, v95
	v_cvt_pk_bf16_f32 v94, v40, v41
	ds_write_b16 v173, v37 offset:18720
	v_cvt_pk_bf16_f32 v37, v39, s0
	v_pk_mul_f32 v[40:41], v[176:177], v[88:89] neg_lo:[0,1] neg_hi:[0,1]
	ds_write_b16 v173, v37 offset:27936
	v_cvt_pk_bf16_f32 v37, v40, s0
	ds_write_b16 v173, v37 offset:288
	v_mul_f32_e32 v37, v83, v97
	v_mul_f32_e32 v39, v79, v97
	v_cvt_pk_bf16_f32 v37, v37, s0
	v_mul_f32_e32 v81, v178, v36
	ds_write_b16 v173, v37 offset:9648
	v_cvt_pk_bf16_f32 v37, v39, s0
	ds_write_b16 v173, v37 offset:18864
	v_cvt_pk_bf16_f32 v37, v81, s0
	ds_write_b16 v173, v37 offset:28080
	v_add_f32_e32 v37, v184, v47
	v_mul_f32_e32 v37, 0x3fb8aa3b, v37
	v_exp_f32_e32 v37, v37
	v_cvt_pk_bf16_f32 v39, v40, v41
	v_cvt_pk_bf16_f32 v87, v41, s0
	v_cvt_pk_bf16_f32 v81, v76, v77
	v_rcp_f32_e32 v40, v37
	v_mul_f32_e32 v77, v180, v37
	v_pk_mul_f32 v[36:37], v[36:37], v[98:99] neg_lo:[0,1] neg_hi:[0,1]
	v_pk_mul_f32 v[88:89], v[46:47], v[96:97] op_sel_hi:[0,1]
	v_mul_f32_e32 v41, v186, v40
	v_mul_f32_e32 v76, v90, v40
	v_cvt_pk_bf16_f32 v41, v41, s0
	ds_write_b16 v173, v41 offset:9792
	v_cvt_pk_bf16_f32 v41, v76, s0
	v_add_f32_e32 v76, v190, v47
	v_mul_f32_e32 v76, 0x3fb8aa3b, v76
	v_exp_f32_e32 v76, v76
	ds_write_b16 v173, v41 offset:19008
	v_cvt_pk_bf16_f32 v41, v77, s0
	ds_write_b16 v173, v41 offset:28224
	v_rcp_f32_e32 v41, v76
	v_cvt_pk_bf16_f32 v77, v36, s0
	v_pk_mul_f32 v[78:79], v[78:79], v[88:89]
	ds_write_b16 v173, v77 offset:576
	v_mul_f32_e32 v77, v187, v41
	v_cvt_pk_bf16_f32 v95, v78, v79
	v_mul_f32_e32 v78, v91, v41
	v_cvt_pk_bf16_f32 v77, v77, s0
	v_mul_f32_e32 v79, v183, v76
	ds_write_b16 v173, v77 offset:9936
	v_cvt_pk_bf16_f32 v77, v78, s0
	ds_write_b16 v173, v77 offset:19152
	v_cvt_pk_bf16_f32 v77, v79, s0
	ds_write_b16 v173, v77 offset:28368
	v_add_f32_e32 v77, v192, v47
	v_mul_f32_e32 v77, 0x3fb8aa3b, v77
	v_exp_f32_e32 v77, v77
; #define LAS __attribute__((address_space(3)))
; __device__ __forceinline__ unsigned pk2(float lo, float hi) { f32x2_k v = {lo, hi}; bf16x2_k b = __builtin_convertvector(v, bf16x2_k); return __builtin_bit_cast(unsigned, b); }
; __device__ __forceinline__ unsigned f2bf(float f) { return pk2(f, 0.f) & 0xffffu; }
; #define TSUB(k) do { } while (0)
; __device__ __forceinline__ void rwkv_chunk_group(Frame& F, int bc, unsigned long long& tsub) {
;     ...
;             *(LAS bf16*)(L + L_AT + t * LD + ch * 2) = (bf16)f2bf(At); *(LAS bf16*)(L + L_BT + t * LD + ch * 2) = (bf16)f2bf(Bt);
;             *(LAS bf16*)(L + L_KT + t * LD + ch * 2) = (bf16)f2bf(Kt); *(LAS bf16*)(L + L_RT + t * LD + ch * 2) = (bf16)f2bf(Rt);
;             if (tt & 1) { patt[tt >> 1] = pk2(hAt, At); pvt[tt >> 1] = pk2(vv[tt - 1], vv[tt]); pbh[tt >> 1] = pk2(hBh, Bh); pkh[tt >> 1] = pk2(hKh, Kh); }
;             hAt = At; hBh = Bh; hKh = Kh;
;         }
;         *(LAS v4u*)(L + L_ATT + ch * LD + tb * 2) = (v4u){patt[0], patt[1], patt[2], patt[3]};
;         *(LAS v4u*)(L + L_VT + ch * LD + tb * 2) = (v4u){pvt[0], pvt[1], pvt[2], pvt[3]};
;         *(LAS v4u*)(L + L_BH + ch * LD + tb * 2) = (v4u){pbh[0], pbh[1], pbh[2], pbh[3]};
;         *(LAS v4u*)(L + L_KH + ch * LD + tb * 2) = (v4u){pkh[0], pkh[1], pkh[2], pkh[3]};
;         LBAR();
;     }
;     TSUB(2);
; #pragma unroll
;     for (int q = 0; q < 2; ++q) { const int tw = 2 * w + q, p0 = 16 * (tw >> 2), q0 = 16 * (tw & 3);
;         f32x4 m = mm_tile(L + L_AT, LD, q0, L + L_BT, LD, p0, 2, Z4, fr, fq);
;         f32x4 nak = mm_tile(L + L_KT, LD, q0, L + L_AT, LD, p0, 2, Z4, fr, fq);
;         f32x4 nrk = mm_tile(L + L_KT, LD, q0, L + L_RT, LD, p0, 2, Z4, fr, fq);
;         f32x4 nrb = mm_tile(L + L_BT, LD, q0, L + L_RT, LD, p0, 2, Z4, fr, fq);
;         f32x4 tt;
;         const int p = p0 + fr;
; #pragma unroll
;         for (int v = 0; v < 4; ++v) { const int qq = q0 + 4 * fq + v;
;             if (!(p < qq)) m[v] = 0.f;
;             if (!(qq < p)) nak[v] = 0.f;
;             if (!(qq <= p)) { nrk[v] = 0.f; nrb[v] = 0.f; }
;             tt[v] = (p == qq) ? 1.f : 0.f; }
;         const int o = p * LD + (q0 + 4 * fq) * 2;
;         st4_lds(L + L_M + o, m); st4t_lds(L + L_MT, p, q0 + 4 * fq, m); st4_lds(L + L_NAK + o, nak); st4_lds(L + L_NRK + o, nrk); st4_lds(L + L_NRB + o, nrb); st4_lds(L + L_TT + o, tt);
;     }
;     LBAR();
	v_pk_mul_f32 v[40:41], v[46:47], v[40:41] op_sel_hi:[0,1]
	v_pk_mul_f32 v[82:83], v[82:83], v[88:89]
	v_pk_mul_f32 v[78:79], v[90:91], v[40:41]
	v_pk_mul_f32 v[88:89], v[186:187], v[40:41]
	v_cvt_pk_bf16_f32 v40, v36, v37
	v_rcp_f32_e32 v36, v77
	ds_write_b16 v173, v87 offset:432
	v_cvt_pk_bf16_f32 v87, v82, v83
	v_cvt_pk_bf16_f32 v82, v37, s0
	v_mul_f32_e32 v37, v100, v36
	v_mul_f32_e32 v41, v42, v36
	v_cvt_pk_bf16_f32 v37, v37, s0
	ds_write_b16 v173, v37 offset:10080
	v_cvt_pk_bf16_f32 v37, v41, s0
	v_add_f32_e32 v41, v52, v47
	v_mul_f32_e32 v41, 0x3fb8aa3b, v41
	v_exp_f32_e32 v41, v41
	v_cvt_pk_bf16_f32 v96, v78, v79
	v_mul_f32_e32 v78, v188, v77
	ds_write_b16 v173, v37 offset:19296
	v_cvt_pk_bf16_f32 v37, v78, s0
	ds_write_b16 v173, v37 offset:28512
	v_rcp_f32_e32 v37, v41
	v_pk_mul_f32 v[44:45], v[76:77], v[44:45] neg_lo:[0,1] neg_hi:[0,1]
	v_mul_f32_e32 v41, v191, v41
	v_cvt_pk_bf16_f32 v47, v44, s0
	ds_write_b16 v173, v47 offset:864
	v_mul_f32_e32 v47, v101, v37
	v_mul_f32_e32 v52, v43, v37
	v_cvt_pk_bf16_f32 v47, v47, s0
	ds_write_b16 v173, v47 offset:10224
	v_cvt_pk_bf16_f32 v47, v52, s0
	v_cvt_pk_bf16_f32 v41, v41, s0
	v_pk_mul_f32 v[36:37], v[46:47], v[36:37] op_sel_hi:[0,1]
	v_cvt_pk_bf16_f32 v76, v45, s0
	ds_write_b16 v173, v41 offset:28656
	v_pk_mul_f32 v[42:43], v[42:43], v[36:37]
	v_pk_mul_f32 v[36:37], v[100:101], v[36:37]
	v_cvt_pk_bf16_f32 v41, v44, v45
	ds_write_b16 v173, v82 offset:720
	v_cvt_pk_bf16_f32 v82, v84, v85
	v_cvt_pk_bf16_f32 v88, v88, v89
	ds_write_b16 v173, v76 offset:1008
	ds_write_b16 v173, v47 offset:19440
	v_cvt_pk_bf16_f32 v97, v42, v43
	v_cvt_pk_bf16_f32 v89, v36, v37
	v_cvt_pk_bf16_f32 v83, v92, v93
	ds_write_b128 v141, v[38:41] offset:36864
	ds_write_b128 v141, v[80:83] offset:46080
	ds_write_b128 v141, v[86:89] offset:55296
	ds_write_b128 v141, v[94:97] offset:64512
	s_waitcnt lgkmcnt(0)
	s_barrier
	v_add_u32_e32 v76, v106, v110
	v_add_u32_e32 v77, v106, v128
	v_add_u32_e32 v97, 0x12000, v127
	v_add_u32_e32 v98, 0x12000, v129
	ds_read_b128 v[176:179], v76 offset:0
	ds_read_b128 v[224:227], v107 offset:9216
	ds_read_b128 v[184:187], v76 offset:18432
	ds_read_b128 v[232:235], v107 offset:0
	ds_read_b128 v[240:243], v107 offset:27648
	ds_read_b128 v[192:195], v76 offset:9216
	ds_read_b128 v[180:183], v76 offset:64
	ds_read_b128 v[228:231], v107 offset:9280
	ds_read_b128 v[188:191], v76 offset:18496
	ds_read_b128 v[236:239], v107 offset:64
	ds_read_b128 v[244:247], v107 offset:27712
	ds_read_b128 v[196:199], v76 offset:9280
	s_waitcnt lgkmcnt(10)
	v_mfma_f32_16x16x32_bf16 v[78:81], v[176:179], v[224:227], 0
	s_waitcnt lgkmcnt(8)
	v_mfma_f32_16x16x32_bf16 v[82:85], v[184:187], v[232:235], 0
	s_waitcnt lgkmcnt(7)
	v_mfma_f32_16x16x32_bf16 v[86:89], v[184:187], v[240:243], 0
	s_waitcnt lgkmcnt(6)
	v_mfma_f32_16x16x32_bf16 v[90:93], v[192:195], v[240:243], 0
	s_waitcnt lgkmcnt(4)
	v_mfma_f32_16x16x32_bf16 v[78:81], v[180:183], v[228:231], v[78:81]
	s_waitcnt lgkmcnt(2)
	v_mfma_f32_16x16x32_bf16 v[82:85], v[188:191], v[236:239], v[82:85]
	s_waitcnt lgkmcnt(1)
	v_mfma_f32_16x16x32_bf16 v[86:89], v[188:191], v[244:247], v[86:89]
	s_waitcnt lgkmcnt(0)
	v_mfma_f32_16x16x32_bf16 v[90:93], v[196:199], v[244:247], v[90:93]
	ds_read_b128 v[176:179], v77 offset:0
	ds_read_b128 v[184:187], v77 offset:18432
	ds_read_b128 v[192:195], v77 offset:9216
	ds_read_b128 v[180:183], v77 offset:64
	ds_read_b128 v[188:191], v77 offset:18496
	ds_read_b128 v[196:199], v77 offset:9280
	s_nop 1
	v_cndmask_b32_e64 v78, 0, v78, s[48:49]
	v_cndmask_b32_e64 v79, v79, 0, s[50:51]
	v_cndmask_b32_e64 v80, 0, v80, s[52:53]
	v_cndmask_b32_e64 v81, 0, v81, s[54:55]
	v_cndmask_b32_e64 v82, 0, v82, s[50:51]
	v_cndmask_b32_e64 v83, 0, v83, s[40:41]
	v_cndmask_b32_e64 v84, 0, v84, s[38:39]
	v_cndmask_b32_e64 v85, 0, v85, s[36:37]
	v_cndmask_b32_e64 v86, v86, 0, s[48:49]
	v_cndmask_b32_e64 v87, 0, v87, s[50:51]
	v_cndmask_b32_e64 v88, v88, 0, s[52:53]
	v_cndmask_b32_e64 v89, v89, 0, s[54:55]
	v_cndmask_b32_e64 v90, v90, 0, s[48:49]
	v_cndmask_b32_e64 v91, 0, v91, s[50:51]
	v_cndmask_b32_e64 v92, v92, 0, s[52:53]
	v_cndmask_b32_e64 v93, v93, 0, s[54:55]
	v_cvt_pk_bf16_f32 v78, v78, v79
	v_cvt_pk_bf16_f32 v79, v80, v81
	v_cvt_pk_bf16_f32 v82, v82, v83
	v_cvt_pk_bf16_f32 v83, v84, v85
	v_cvt_pk_bf16_f32 v86, v86, v87
	v_cvt_pk_bf16_f32 v87, v88, v89
	v_cvt_pk_bf16_f32 v90, v90, v91
	v_cvt_pk_bf16_f32 v91, v92, v93
	ds_write_b64 v97, v[78:79]
	ds_write_b64 v97, v[82:83] offset:27648
	ds_write_b64 v97, v[86:87] offset:36864
	ds_write_b64 v97, v[90:91] offset:46080
	ds_write_b64 v97, v[60:61] offset:18432
	s_waitcnt lgkmcnt(10)
	v_mfma_f32_16x16x32_bf16 v[36:39], v[176:179], v[224:227], 0
	s_waitcnt lgkmcnt(9)
	v_mfma_f32_16x16x32_bf16 v[40:43], v[184:187], v[232:235], 0
	s_waitcnt lgkmcnt(9)
	v_mfma_f32_16x16x32_bf16 v[44:47], v[184:187], v[240:243], 0
	s_waitcnt lgkmcnt(8)
	v_mfma_f32_16x16x32_bf16 v[100:103], v[192:195], v[240:243], 0
	s_waitcnt lgkmcnt(7)
	v_mfma_f32_16x16x32_bf16 v[36:39], v[180:183], v[228:231], v[36:39]
	s_waitcnt lgkmcnt(6)
	v_mfma_f32_16x16x32_bf16 v[40:43], v[188:191], v[236:239], v[40:43]
	s_waitcnt lgkmcnt(6)
	v_mfma_f32_16x16x32_bf16 v[44:47], v[188:191], v[244:247], v[44:47]
	s_waitcnt lgkmcnt(5)
	v_mfma_f32_16x16x32_bf16 v[100:103], v[196:199], v[244:247], v[100:103]
	s_nop 7
	v_cndmask_b32_e64 v36, 0, v36, s[56:57]
	v_cndmask_b32_e64 v37, v37, 0, s[58:59]
	v_cndmask_b32_e64 v38, 0, v38, s[60:61]
	v_cndmask_b32_e64 v39, 0, v39, s[62:63]
	v_cndmask_b32_e64 v40, 0, v40, s[58:59]
	v_cndmask_b32_e64 v41, 0, v41, s[46:47]
	v_cndmask_b32_e64 v42, 0, v42, s[44:45]
	v_cndmask_b32_e64 v43, 0, v43, s[42:43]
	v_cndmask_b32_e64 v44, v44, 0, s[56:57]
	v_cndmask_b32_e64 v45, 0, v45, s[58:59]
	v_cndmask_b32_e64 v46, v46, 0, s[60:61]
	v_cndmask_b32_e64 v47, v47, 0, s[62:63]
	v_cndmask_b32_e64 v100, v100, 0, s[56:57]
	v_cndmask_b32_e64 v101, 0, v101, s[58:59]
	v_cndmask_b32_e64 v102, v102, 0, s[60:61]
	v_cndmask_b32_e64 v103, v103, 0, s[62:63]
	v_cvt_pk_bf16_f32 v36, v36, v37
	v_cvt_pk_bf16_f32 v37, v38, v39
	v_cvt_pk_bf16_f32 v40, v40, v41
	v_cvt_pk_bf16_f32 v41, v42, v43
	v_cvt_pk_bf16_f32 v44, v44, v45
	v_cvt_pk_bf16_f32 v45, v46, v47
	v_cvt_pk_bf16_f32 v100, v100, v101
	v_cvt_pk_bf16_f32 v101, v102, v103
	ds_write_b64 v98, v[36:37]
	ds_write_b64 v98, v[40:41] offset:27648
	ds_write_b64 v98, v[44:45] offset:36864
	ds_write_b64 v98, v[100:101] offset:46080
	ds_write_b64 v98, v[72:73] offset:18432

; __device__ __forceinline__ void st4_lds(LAS unsigned char* p, f32x4 v) { v2u w; w.x = pk2(v[0], v[1]); w.y = pk2(v[2], v[3]); *(LAS v2u*)p = w; }
; __device__ __forceinline__ f32x4 ld4_lds(const LAS unsigned char* p) { const v2u w = *(const LAS v2u*)p; return (f32x4){bflo(w.x), bfhi(w.x), bflo(w.y), bfhi(w.y)}; }
; #define LBAR() asm volatile("s_waitcnt lgkmcnt(0)\n\ts_barrier" ::: "memory")
; __device__ __forceinline__ void rwkv_chunk_group(Frame& F, int bc, unsigned long long& tsub) {
;     ...
;     for (int it = 0; it < 6; ++it) {
;         const int rM = (it & 1) ? L_AT : L_M, rMT = (it & 1) ? L_BT : L_MT, rTT = (it & 1) ? L_KT : L_TT;
;         const int wM = (it & 1) ? L_M : L_AT, wMT = (it & 1) ? L_MT : L_BT, wTT = (it & 1) ? L_TT : L_KT;
; #pragma unroll
;         for (int q = 0; q < 2; ++q) { const int tw = 2 * w + q, p0 = 16 * (tw >> 2), q0 = 16 * (tw & 3); const int o = (p0 + fr) * LD + (q0 + 4 * fq) * 2;
;             f32x4 tn = Z4, mn = Z4;
;             if (q0 <= p0) { tn = mm_tile(L + rM, LD, q0, L + rTT, LD, p0, 2, ld4_lds(L + rTT + o), fr, fq);
;                           }
;             if (q0 >= p0 && it < 5) mn = mm_tile(L + rMT, LD, q0, L + rM, LD, p0, 2, Z4, fr, fq);
;             st4_lds(L + wTT + o, tn); if (it < 5) { st4_lds(L + wM + o, mn); st4t_lds(L + wMT, p0 + fr, q0 + 4 * fq, mn); } }
;         LBAR();
;     }
	s_waitcnt lgkmcnt(0)
	s_barrier
	v_mov_b32_e32 v78, v127
	v_mov_b32_e32 v79, v129
	v_add_u32_e32 v173, v106, v110
	v_add_u32_e32 v174, v106, v128
	v_add_u32_e32 v97, 0x12000, v127
	v_add_u32_e32 v98, 0x12000, v129
	v_mov_b32_e32 v102, 0
	v_mov_b32_e32 v103, 0
	v_add_u32_e32 v175, 0x12000, v173
	v_add_u32_e32 v96, 0x12000, v174
	s_and_b64 vcc, exec, s[78:79]
	s_cbranch_vccz .La2_FTFT
	s_and_b64 vcc, exec, s[84:85]
	s_cbranch_vccz .La2_TFTx
	ds_read_b64 v[242:243], v97 offset:18432
	ds_read_b128 v[176:179], v175 offset:0
	ds_read_b128 v[224:227], v132 offset:18432
	ds_read_b64_tr_b16 v[184:185], v253 offset:0
	ds_read_b64_tr_b16 v[186:187], v253 offset:576
	ds_read_b128 v[232:235], v132 offset:0
	ds_read_b64_tr_b16 v[192:193], v253 offset:32
	ds_read_b64_tr_b16 v[194:195], v253 offset:608
	ds_read_b128 v[180:183], v175 offset:64
	ds_read_b128 v[228:231], v132 offset:18496
	ds_read_b64_tr_b16 v[188:189], v253 offset:4608
	ds_read_b64_tr_b16 v[190:191], v253 offset:5184
	ds_read_b128 v[236:239], v132 offset:64
	ds_read_b64_tr_b16 v[196:197], v253 offset:4640
	ds_read_b64_tr_b16 v[198:199], v253 offset:5216
	s_waitcnt lgkmcnt(14)
	v_lshlrev_b32_e32 v240, 16, v242
	v_and_b32_e32 v241, 0xffff0000, v242
	v_lshlrev_b32_e32 v242, 16, v243
	v_and_b32_e32 v243, 0xffff0000, v243
	s_nop 1
	s_waitcnt lgkmcnt(12)
	v_mfma_f32_16x16x32_bf16 v[240:243], v[176:179], v[224:227], v[240:243]
	s_waitcnt lgkmcnt(9)
	v_mfma_f32_16x16x32_bf16 v[244:247], v[184:187], v[232:235], 0
	s_waitcnt lgkmcnt(7)
	v_mfma_f32_16x16x32_bf16 v[248:251], v[192:195], v[232:235], 0
	s_waitcnt lgkmcnt(5)
	v_mfma_f32_16x16x32_bf16 v[240:243], v[180:183], v[228:231], v[240:243]
	s_waitcnt lgkmcnt(2)
	v_mfma_f32_16x16x32_bf16 v[244:247], v[188:191], v[236:239], v[244:247]
	s_waitcnt lgkmcnt(0)
	v_mfma_f32_16x16x32_bf16 v[248:251], v[196:199], v[236:239], v[248:251]
	s_nop 7
	v_cvt_pk_bf16_f32 v176, v240, v241
	v_cvt_pk_bf16_f32 v177, v242, v243
	v_cvt_pk_bf16_f32 v184, v244, v245
	v_cvt_pk_bf16_f32 v185, v246, v247
	v_cvt_pk_bf16_f32 v192, v248, v249
	v_cvt_pk_bf16_f32 v193, v250, v251
	ds_write_b64 v127, v[176:177] offset:18432
	ds_write_b64 v127, v[184:185] offset:0
	ds_write_b64 v129, v[102:103] offset:18432
	ds_write_b64 v129, v[192:193] offset:0
	s_waitcnt lgkmcnt(0)
	s_barrier
	ds_read_b64 v[242:243], v127 offset:18432
	ds_read_b128 v[176:179], v173 offset:0
	ds_read_b128 v[224:227], v107 offset:18432
	ds_read_b64_tr_b16 v[184:185], v252 offset:0
	ds_read_b64_tr_b16 v[186:187], v252 offset:576
	ds_read_b128 v[232:235], v107 offset:0
	ds_read_b64_tr_b16 v[192:193], v252 offset:32
	ds_read_b64_tr_b16 v[194:195], v252 offset:608
	ds_read_b128 v[180:183], v173 offset:64
	ds_read_b128 v[228:231], v107 offset:18496
	ds_read_b64_tr_b16 v[188:189], v252 offset:4608
	ds_read_b64_tr_b16 v[190:191], v252 offset:5184
	ds_read_b128 v[236:239], v107 offset:64
	ds_read_b64_tr_b16 v[196:197], v252 offset:4640
	ds_read_b64_tr_b16 v[198:199], v252 offset:5216
	s_waitcnt lgkmcnt(14)
	v_lshlrev_b32_e32 v240, 16, v242
	v_and_b32_e32 v241, 0xffff0000, v242
	v_lshlrev_b32_e32 v242, 16, v243
	v_and_b32_e32 v243, 0xffff0000, v243
	s_nop 1
	s_waitcnt lgkmcnt(12)
	v_mfma_f32_16x16x32_bf16 v[240:243], v[176:179], v[224:227], v[240:243]
	s_waitcnt lgkmcnt(9)
	v_mfma_f32_16x16x32_bf16 v[244:247], v[184:187], v[232:235], 0
	s_waitcnt lgkmcnt(7)
	v_mfma_f32_16x16x32_bf16 v[248:251], v[192:195], v[232:235], 0
	s_waitcnt lgkmcnt(5)
	v_mfma_f32_16x16x32_bf16 v[240:243], v[180:183], v[228:231], v[240:243]
	s_waitcnt lgkmcnt(2)
	v_mfma_f32_16x16x32_bf16 v[244:247], v[188:191], v[236:239], v[244:247]
	s_waitcnt lgkmcnt(0)
	v_mfma_f32_16x16x32_bf16 v[248:251], v[196:199], v[236:239], v[248:251]
	s_nop 7
	v_cvt_pk_bf16_f32 v176, v240, v241
	v_cvt_pk_bf16_f32 v177, v242, v243
	v_cvt_pk_bf16_f32 v184, v244, v245
	v_cvt_pk_bf16_f32 v185, v246, v247
	v_cvt_pk_bf16_f32 v192, v248, v249
	v_cvt_pk_bf16_f32 v193, v250, v251
	ds_write_b64 v97, v[176:177] offset:18432
	ds_write_b64 v97, v[184:185] offset:0
	ds_write_b64 v98, v[192:193] offset:0
	s_waitcnt lgkmcnt(0)
	s_barrier
	ds_read_b64 v[242:243], v97 offset:18432
	ds_read_b128 v[176:179], v175 offset:0
	ds_read_b128 v[224:227], v132 offset:18432
	ds_read_b64_tr_b16 v[184:185], v253 offset:0
	ds_read_b64_tr_b16 v[186:187], v253 offset:576
	ds_read_b128 v[232:235], v132 offset:0
	ds_read_b64_tr_b16 v[192:193], v253 offset:32
	ds_read_b64_tr_b16 v[194:195], v253 offset:608
	ds_read_b128 v[180:183], v175 offset:64
	ds_read_b128 v[228:231], v132 offset:18496
	ds_read_b64_tr_b16 v[188:189], v253 offset:4608
	ds_read_b64_tr_b16 v[190:191], v253 offset:5184
	ds_read_b128 v[236:239], v132 offset:64
	ds_read_b64_tr_b16 v[196:197], v253 offset:4640
	ds_read_b64_tr_b16 v[198:199], v253 offset:5216
	s_waitcnt lgkmcnt(14)
	v_lshlrev_b32_e32 v240, 16, v242
	v_and_b32_e32 v241, 0xffff0000, v242
	v_lshlrev_b32_e32 v242, 16, v243
	v_and_b32_e32 v243, 0xffff0000, v243
	s_nop 1
	s_waitcnt lgkmcnt(12)
	v_mfma_f32_16x16x32_bf16 v[240:243], v[176:179], v[224:227], v[240:243]
	s_waitcnt lgkmcnt(9)
	v_mfma_f32_16x16x32_bf16 v[244:247], v[184:187], v[232:235], 0
	s_waitcnt lgkmcnt(7)
	v_mfma_f32_16x16x32_bf16 v[248:251], v[192:195], v[232:235], 0
	s_waitcnt lgkmcnt(5)
	v_mfma_f32_16x16x32_bf16 v[240:243], v[180:183], v[228:231], v[240:243]
	s_waitcnt lgkmcnt(2)
	v_mfma_f32_16x16x32_bf16 v[244:247], v[188:191], v[236:239], v[244:247]
	s_waitcnt lgkmcnt(0)
	v_mfma_f32_16x16x32_bf16 v[248:251], v[196:199], v[236:239], v[248:251]
	s_nop 7
	v_cvt_pk_bf16_f32 v176, v240, v241
	v_cvt_pk_bf16_f32 v177, v242, v243
	v_cvt_pk_bf16_f32 v184, v244, v245
	v_cvt_pk_bf16_f32 v185, v246, v247
	v_cvt_pk_bf16_f32 v192, v248, v249
	v_cvt_pk_bf16_f32 v193, v250, v251
	ds_write_b64 v127, v[176:177] offset:18432
	ds_write_b64 v127, v[184:185] offset:0
	ds_write_b64 v129, v[192:193] offset:0
	s_waitcnt lgkmcnt(0)
	s_barrier
; __device__ __forceinline__ void st4_lds(LAS unsigned char* p, f32x4 v) { v2u w; w.x = pk2(v[0], v[1]); w.y = pk2(v[2], v[3]); *(LAS v2u*)p = w; }
; __device__ __forceinline__ f32x4 ld4_lds(const LAS unsigned char* p) { const v2u w = *(const LAS v2u*)p; return (f32x4){bflo(w.x), bfhi(w.x), bflo(w.y), bfhi(w.y)}; }
; #define LBAR() asm volatile("s_waitcnt lgkmcnt(0)\n\ts_barrier" ::: "memory")
; __device__ __forceinline__ void rwkv_chunk_group(Frame& F, int bc, unsigned long long& tsub) {
;     ...
;     for (int it = 0; it < 6; ++it) {
;         const int rM = (it & 1) ? L_AT : L_M, rMT = (it & 1) ? L_BT : L_MT, rTT = (it & 1) ? L_KT : L_TT;
;         const int wM = (it & 1) ? L_M : L_AT, wMT = (it & 1) ? L_MT : L_BT, wTT = (it & 1) ? L_TT : L_KT;
; #pragma unroll
;         for (int q = 0; q < 2; ++q) { const int tw = 2 * w + q, p0 = 16 * (tw >> 2), q0 = 16 * (tw & 3); const int o = (p0 + fr) * LD + (q0 + 4 * fq) * 2;
;             f32x4 tn = Z4, mn = Z4;
;             if (q0 <= p0) { tn = mm_tile(L + rM, LD, q0, L + rTT, LD, p0, 2, ld4_lds(L + rTT + o), fr, fq);
;                           }
;             if (q0 >= p0 && it < 5) mn = mm_tile(L + rMT, LD, q0, L + rM, LD, p0, 2, Z4, fr, fq);
;             st4_lds(L + wTT + o, tn); if (it < 5) { st4_lds(L + wM + o, mn); st4t_lds(L + wMT, p0 + fr, q0 + 4 * fq, mn); } }
;         LBAR();
;     }
	ds_read_b64 v[242:243], v127 offset:18432
	ds_read_b128 v[176:179], v173 offset:0
	ds_read_b128 v[224:227], v107 offset:18432
	ds_read_b64_tr_b16 v[184:185], v252 offset:0
	ds_read_b64_tr_b16 v[186:187], v252 offset:576
	ds_read_b128 v[232:235], v107 offset:0
	ds_read_b64_tr_b16 v[192:193], v252 offset:32
	ds_read_b64_tr_b16 v[194:195], v252 offset:608
	ds_read_b128 v[180:183], v173 offset:64
	ds_read_b128 v[228:231], v107 offset:18496
	ds_read_b64_tr_b16 v[188:189], v252 offset:4608
	ds_read_b64_tr_b16 v[190:191], v252 offset:5184
	ds_read_b128 v[236:239], v107 offset:64
	ds_read_b64_tr_b16 v[196:197], v252 offset:4640
	ds_read_b64_tr_b16 v[198:199], v252 offset:5216
	s_waitcnt lgkmcnt(14)
	v_lshlrev_b32_e32 v240, 16, v242
	v_and_b32_e32 v241, 0xffff0000, v242
	v_lshlrev_b32_e32 v242, 16, v243
	v_and_b32_e32 v243, 0xffff0000, v243
	s_nop 1
	s_waitcnt lgkmcnt(12)
	v_mfma_f32_16x16x32_bf16 v[240:243], v[176:179], v[224:227], v[240:243]
	s_waitcnt lgkmcnt(9)
	v_mfma_f32_16x16x32_bf16 v[244:247], v[184:187], v[232:235], 0
	s_waitcnt lgkmcnt(7)
	v_mfma_f32_16x16x32_bf16 v[248:251], v[192:195], v[232:235], 0
	s_waitcnt lgkmcnt(5)
	v_mfma_f32_16x16x32_bf16 v[240:243], v[180:183], v[228:231], v[240:243]
	s_waitcnt lgkmcnt(2)
	v_mfma_f32_16x16x32_bf16 v[244:247], v[188:191], v[236:239], v[244:247]
	s_waitcnt lgkmcnt(0)
	v_mfma_f32_16x16x32_bf16 v[248:251], v[196:199], v[236:239], v[248:251]
	s_nop 7
	v_cvt_pk_bf16_f32 v176, v240, v241
	v_cvt_pk_bf16_f32 v177, v242, v243
	v_cvt_pk_bf16_f32 v184, v244, v245
	v_cvt_pk_bf16_f32 v185, v246, v247
	v_cvt_pk_bf16_f32 v192, v248, v249
	v_cvt_pk_bf16_f32 v193, v250, v251
	ds_write_b64 v97, v[176:177] offset:18432
	ds_write_b64 v97, v[184:185] offset:0
	ds_write_b64 v98, v[192:193] offset:0
	s_waitcnt lgkmcnt(0)
	s_barrier
	ds_read_b64 v[242:243], v97 offset:18432
	ds_read_b128 v[176:179], v175 offset:0
	ds_read_b128 v[224:227], v132 offset:18432
	ds_read_b64_tr_b16 v[184:185], v253 offset:0
	ds_read_b64_tr_b16 v[186:187], v253 offset:576
	ds_read_b128 v[232:235], v132 offset:0
	ds_read_b64_tr_b16 v[192:193], v253 offset:32
	ds_read_b64_tr_b16 v[194:195], v253 offset:608
	ds_read_b128 v[180:183], v175 offset:64
	ds_read_b128 v[228:231], v132 offset:18496
	ds_read_b64_tr_b16 v[188:189], v253 offset:4608
	ds_read_b64_tr_b16 v[190:191], v253 offset:5184
	ds_read_b128 v[236:239], v132 offset:64
	ds_read_b64_tr_b16 v[196:197], v253 offset:4640
	ds_read_b64_tr_b16 v[198:199], v253 offset:5216
	s_waitcnt lgkmcnt(14)
	v_lshlrev_b32_e32 v240, 16, v242
	v_and_b32_e32 v241, 0xffff0000, v242
	v_lshlrev_b32_e32 v242, 16, v243
	v_and_b32_e32 v243, 0xffff0000, v243
	s_nop 1
	s_waitcnt lgkmcnt(12)
	v_mfma_f32_16x16x32_bf16 v[240:243], v[176:179], v[224:227], v[240:243]
	s_waitcnt lgkmcnt(9)
	v_mfma_f32_16x16x32_bf16 v[244:247], v[184:187], v[232:235], 0
	s_waitcnt lgkmcnt(7)
	v_mfma_f32_16x16x32_bf16 v[248:251], v[192:195], v[232:235], 0
	s_waitcnt lgkmcnt(5)
	v_mfma_f32_16x16x32_bf16 v[240:243], v[180:183], v[228:231], v[240:243]
	s_waitcnt lgkmcnt(2)
	v_mfma_f32_16x16x32_bf16 v[244:247], v[188:191], v[236:239], v[244:247]
	s_waitcnt lgkmcnt(0)
	v_mfma_f32_16x16x32_bf16 v[248:251], v[196:199], v[236:239], v[248:251]
	s_nop 7
	v_cvt_pk_bf16_f32 v176, v240, v241
	v_cvt_pk_bf16_f32 v177, v242, v243
	v_cvt_pk_bf16_f32 v184, v244, v245
	v_cvt_pk_bf16_f32 v185, v246, v247
	v_cvt_pk_bf16_f32 v192, v248, v249
	v_cvt_pk_bf16_f32 v193, v250, v251
	ds_write_b64 v127, v[176:177] offset:18432
	ds_write_b64 v127, v[184:185] offset:0
	ds_write_b64 v129, v[192:193] offset:0
	s_waitcnt lgkmcnt(0)
	s_barrier
	ds_read_b64 v[242:243], v127 offset:18432
	ds_read_b128 v[176:179], v173 offset:0
	ds_read_b128 v[224:227], v107 offset:18432
	ds_read_b128 v[180:183], v173 offset:64
	ds_read_b128 v[228:231], v107 offset:18496
	s_waitcnt lgkmcnt(4)
	v_lshlrev_b32_e32 v240, 16, v242
	v_and_b32_e32 v241, 0xffff0000, v242
	v_lshlrev_b32_e32 v242, 16, v243
	v_and_b32_e32 v243, 0xffff0000, v243
	s_nop 1
	s_waitcnt lgkmcnt(2)
	v_mfma_f32_16x16x32_bf16 v[240:243], v[176:179], v[224:227], v[240:243]
	s_waitcnt lgkmcnt(0)
	v_mfma_f32_16x16x32_bf16 v[240:243], v[180:183], v[228:231], v[240:243]
	s_nop 7
	v_cvt_pk_bf16_f32 v176, v240, v241
	v_cvt_pk_bf16_f32 v177, v242, v243
	ds_write_b64 v97, v[176:177] offset:18432
	s_waitcnt lgkmcnt(0)
	s_barrier
	s_branch .La2_done

; __device__ __forceinline__ void lora_dma(const bf16* lora, int h, unsigned lds0, int w, int lane) {
;     ...
;         if (p < 16) { const int row = 8 * (p & 7) + (lane >> 3); src = lora + (p >= 8 ? 512 * 64 : 0) + (size_t)(h * 64 + row) * 64 + (lane & 7) * 8; dst = lds0 + L_LWA + p * 1024; }
;         else { const int q = p - 16, ks = q >> 2, row = 16 * (q & 3) + (lane >> 2); src = lora + 2 * 512 * 64 + (size_t)(h * 64 + row) * 160 + ks * 32 + (lane & 3) * 8; dst = lds0 + L_LG + q * 1024; }
; __device__ __forceinline__ void rwkv_chunk_group(Frame& F, int bc, unsigned long long& tsub) {
;     ...
;     if (hh + 1 < RW_H) lora_dma(lora, hnext, lds0, w, lane);
.La2_done:
	v_readlane_b32 s14, v254, 25
	v_readlane_b32 s15, v254, 26
	s_or_b64 s[14:15], s[14:15], s[96:97]
	s_and_b64 vcc, exec, s[14:15]
	s_cbranch_vccnz .LBB0_1411
	v_readlane_b32 s14, v254, 57
	s_lshl_b32 s13, s13, 6

; __device__ __forceinline__ void lora_dma(const bf16* lora, int h, unsigned lds0, int w, int lane) {
;     for (int p = w; p < 36; p += NWAVES) {
;         const bf16* src; unsigned dst;
;         if (p < 16) { const int row = 8 * (p & 7) + (lane >> 3); src = lora + (p >= 8 ? 512 * 64 : 0) + (size_t)(h * 64 + row) * 64 + (lane & 7) * 8; dst = lds0 + L_LWA + p * 1024; }
;         else { const int q = p - 16, ks = q >> 2, row = 16 * (q & 3) + (lane >> 2); src = lora + 2 * 512 * 64 + (size_t)(h * 64 + row) * 160 + ks * 32 + (lane & 3) * 8; dst = lds0 + L_LG + q * 1024; }
;         attn_body::glds16(src, (unsigned)__builtin_amdgcn_readfirstlane(dst));
	v_add_u32_e32 v40, s13, v51
	v_add_u32_e32 v41, s13, v59
	s_mov_b32 s13, s14
	v_readlane_b32 s14, v254, 23
	s_mov_b32 s15, s17
	s_branch .LBB0_1465
